# speedup vs baseline: 1.0257x; 1.0085x over previous
; __device__ __forceinline__ float bflo(unsigned w) { return __uint_as_float(w << 16); }
; __device__ __forceinline__ float bfhi(unsigned w) { return __uint_as_float(w & 0xffff0000u); }
; __device__ __forceinline__ float lane_read(float v, int src) { return __int_as_float(__builtin_amdgcn_ds_bpermute(src << 2, __float_as_int(v))); }
; __device__ __forceinline__ void load_q_roped(const bf16_t* Qw, const float* __restrict__ wq, const float* __restrict__ RT, int pr, int pc, int hi, int lane, bf16x8 (&qr)[8]) {
;   float y[8][8]; float ss = 0.f;
; #pragma unroll
;   for (int d0 = 0; d0 < 8; ++d0) { const u32x4 w = *(const u32x4*)(Qw + d0 * 16);
; #pragma unroll
;     for (int q = 0; q < 4; ++q) { y[d0][2 * q] = bflo(w[q]); y[d0][2 * q + 1] = bfhi(w[q]); } }
; #pragma unroll
;   for (int d0 = 0; d0 < 8; ++d0)
; #pragma unroll
;     for (int e = 0; e < 8; ++e) ss += y[d0][e] * y[d0][e];
;   ss += lane_read(ss, lane ^ 32);
;   const float rstd = __builtin_amdgcn_rsqf(ss * (1.f / 128.f) + 1e-6f);
; #pragma unroll
;   for (int d0 = 0; d0 < 8; ++d0) { const f32x4 w0 = *(const f32x4*)(wq + d0 * 16), w1 = *(const f32x4*)(wq + d0 * 16 + 4);
; #pragma unroll
;     for (int e = 0; e < 8; ++e) y[d0][e] *= rstd * (e < 4 ? w0[e & 3] : w1[e & 3]); }
; #pragma unroll
;   for (int hf = 0; hf < 2; ++hf)
; #pragma unroll
;     for (int lo = 0; lo < 2; ++lo) { const int d0 = hf * 4 + lo;
;       const float* tp = RT + (size_t)((hf ? pc : pr) * 32 + lo * 16 + hi * 8) * 2;
;       f32x4 t[4];
; #pragma unroll
;       for (int q = 0; q < 4; ++q) t[q] = *(const f32x4*)(tp + 4 * q);
.LBB0_259:
	s_bfe_u32 s1, s2, 0x10008
	s_ashr_i32 s0, s2, 9
	s_lshl_b32 s3, s1, 8
	v_readlane_b32 s6, v255, 9
	v_readlane_b32 s7, v255, 10
	s_add_u32 s40, s6, s3
	s_addc_u32 s41, s7, 0
	v_readlane_b32 s6, v255, 5
	v_readlane_b32 s7, v255, 6
	s_add_u32 s42, s6, s3
	s_addc_u32 s43, s7, 0
	s_lshl_b32 s3, s2, 6
	s_and_b32 s3, s3, 0x3f00
	v_add_u32_e32 v191, s3, v172
	v_or_b32_e32 v21, v191, v163
	s_lshl_b32 s3, s0, 14
	v_add_u32_e32 v2, s3, v21
	s_lshl_b32 s4, s2, 7
	v_ashrrev_i32_e32 v3, 31, v2
	s_lshl_b32 s1, s1, 9
	s_and_b32 s4, s4, 0x180
	v_lshlrev_b64 v[2:3], 11, v[2:3]
	s_or_b32 s30, s1, s4
	v_lshl_add_u64 v[2:3], s[20:21], 0, v[2:3]
	s_lshl_b32 s4, s30, 1
	v_lshl_add_u64 v[2:3], v[2:3], 0, s[4:5]
	v_lshlrev_b32_e32 v0, 1, v162
	v_lshl_add_u64 v[18:19], v[2:3], 0, v[0:1]
	global_load_dwordx4 v[58:61], v[18:19], off offset:160
	global_load_dwordx4 v[62:65], v[18:19], off offset:224
	global_load_dwordx4 v[66:69], v[18:19], off offset:128
	global_load_dwordx4 v[70:73], v[18:19], off offset:192
	global_load_dwordx4 v[2:5], v[164:165], off
	global_load_dwordx4 v[6:9], v[164:165], off offset:16
	global_load_dwordx4 v[10:13], v[164:165], off offset:64
	global_load_dwordx4 v[82:85], v[164:165], off offset:80
	global_load_dwordx4 v[86:89], v[164:165], off offset:128
	global_load_dwordx4 v[90:93], v[164:165], off offset:144
	global_load_dwordx4 v[94:97], v[164:165], off offset:192
	global_load_dwordx4 v[98:101], v[164:165], off offset:208
	global_load_dwordx4 v[102:105], v[164:165], off offset:256
	global_load_dwordx4 v[106:109], v[164:165], off offset:272
	global_load_dwordx4 v[50:53], v[18:19], off offset:32
	global_load_dwordx4 v[110:113], v[164:165], off offset:320
	global_load_dwordx4 v[114:117], v[164:165], off offset:336
	global_load_dwordx4 v[54:57], v[18:19], off offset:96
	global_load_dwordx4 v[118:121], v[164:165], off offset:384
	global_load_dwordx4 v[122:125], v[164:165], off offset:400
	global_load_dwordx4 v[126:129], v[164:165], off offset:448
	global_load_dwordx4 v[14:17], v[164:165], off offset:464
	global_load_dwordx4 v[74:77], v[18:19], off
	s_lshl_b32 s4, s0, 4
	s_add_i32 s31, s4, 0x8000
	v_ashrrev_i32_e32 v0, 1, v191
	s_movk_i32 s4, 0xffe0
	v_and_or_b32 v20, v0, s4, v162
	v_lshlrev_b32_e32 v0, 5, v21
	v_ashrrev_i32_e32 v21, 31, v20
	v_or_b32_e32 v22, 16, v20
	v_lshl_add_u64 v[20:21], v[20:21], 3, s[48:49]
	global_load_dwordx4 v[78:81], v[18:19], off offset:64
	global_load_dwordx4 v[30:33], v[20:21], off offset:48
	global_load_dwordx4 v[38:41], v[20:21], off offset:32
	global_load_dwordx4 v[42:45], v[20:21], off offset:16
	global_load_dwordx4 v[46:49], v[20:21], off
	s_movk_i32 s4, 0x7e0
	v_and_or_b32 v0, v0, s4, v162
	v_lshlrev_b32_e32 v195, 3, v0
	v_mov_b32_e32 v196, v245
	v_mov_b64_e32 v[244:245], v[242:243]
	v_mov_b64_e32 v[174:175], v[248:249]
	v_ashrrev_i32_e32 v23, 31, v22
	v_lshl_add_u64 v[34:35], v[22:23], 3, s[48:49]
	global_load_dwordx4 v[18:21], v[34:35], off offset:48
	global_load_dwordx4 v[22:25], v[34:35], off offset:32
	global_load_dwordx4 v[26:29], v[34:35], off offset:16
	s_nop 0
	global_load_dwordx4 v[34:37], v[34:35], off
	s_ashr_i32 s1, s0, 31
	s_lshl_b64 s[90:91], s[0:1], 14
	s_ashr_i32 s44, s31, 31
	s_lshl_b64 s[0:1], s[0:1], 23
	s_add_u32 s6, s42, s0
	s_addc_u32 s7, s43, s1
	s_add_u32 s8, s40, s0
	s_addc_u32 s9, s41, s1
	s_mov_b32 s4, s5
	s_mov_b32 s10, s5
	s_mov_b32 s11, s5
	s_mov_b32 s12, s5
	s_mov_b32 s13, s5
	s_mov_b32 s14, s5
	s_mov_b32 s15, s5
	s_mov_b32 s16, s5
	s_mov_b32 s17, s5
	s_mov_b32 s18, s5
	s_mov_b32 s19, s5
	s_mov_b32 s28, 1
	s_waitcnt vmcnt(0)
	v_lshlrev_b32_e32 v142, 16, v58
	v_and_b32_e32 v143, 0xffff0000, v58
	v_lshlrev_b32_e32 v226, 16, v66
	v_and_b32_e32 v227, 0xffff0000, v66
	v_lshlrev_b32_e32 v218, 16, v67
	v_and_b32_e32 v219, 0xffff0000, v67
	v_pk_mul_f32 v[66:67], v[226:227], v[226:227]
	v_pk_mul_f32 v[222:223], v[218:219], v[218:219]
	v_lshlrev_b32_e32 v214, 16, v68
	v_and_b32_e32 v215, 0xffff0000, v68
	v_lshlrev_b32_e32 v144, 16, v69
	v_and_b32_e32 v145, 0xffff0000, v69
	v_pk_mul_f32 v[68:69], v[214:215], v[214:215]
	v_pk_mul_f32 v[210:211], v[144:145], v[144:145]
	v_lshlrev_b32_e32 v202, 16, v51
	v_and_b32_e32 v203, 0xffff0000, v51
	v_lshlrev_b32_e32 v150, 16, v50
	v_and_b32_e32 v151, 0xffff0000, v50
	v_lshlrev_b32_e32 v238, 16, v52
	v_and_b32_e32 v239, 0xffff0000, v52
	v_lshlrev_b32_e32 v230, 16, v53
	v_and_b32_e32 v231, 0xffff0000, v53
	v_lshlrev_b32_e32 v158, 16, v74
	v_and_b32_e32 v159, 0xffff0000, v74
	v_lshlrev_b32_e32 v156, 16, v75
	v_and_b32_e32 v157, 0xffff0000, v75
	v_pk_mul_f32 v[50:51], v[158:159], v[158:159]
	v_lshlrev_b32_e32 v154, 16, v76
	v_add_f32_e32 v0, v50, v51
	v_pk_mul_f32 v[50:51], v[156:157], v[156:157]
	v_and_b32_e32 v155, 0xffff0000, v76
	v_add_f32_e32 v0, v50, v0
	v_add_f32_e32 v0, v51, v0
	v_pk_mul_f32 v[50:51], v[154:155], v[154:155]
	v_lshlrev_b32_e32 v152, 16, v77
	v_and_b32_e32 v153, 0xffff0000, v77
	v_add_f32_e32 v0, v50, v0
	v_add_f32_e32 v0, v51, v0
	v_pk_mul_f32 v[50:51], v[152:153], v[152:153]
	v_pk_mul_f32 v[52:53], v[238:239], v[238:239]
	v_add_f32_e32 v0, v50, v0
	v_add_f32_e32 v0, v51, v0
	v_pk_mul_f32 v[50:51], v[150:151], v[150:151]
	v_pk_mul_f32 v[234:235], v[230:231], v[230:231]
	v_add_f32_e32 v0, v50, v0
	v_add_f32_e32 v0, v51, v0
	v_pk_mul_f32 v[50:51], v[202:203], v[202:203]
	v_lshlrev_b32_e32 v242, 16, v78
	v_add_f32_e32 v0, v50, v0
	v_add_f32_e32 v0, v51, v0
	v_add_f32_e32 v0, v52, v0
	v_add_f32_e32 v0, v53, v0
	v_and_b32_e32 v243, 0xffff0000, v78
	v_add_f32_e32 v0, v234, v0
	v_lshlrev_b32_e32 v198, 16, v55
	v_and_b32_e32 v199, 0xffff0000, v55
	v_lshlrev_b32_e32 v200, 16, v54
	v_and_b32_e32 v201, 0xffff0000, v54
; __device__ __forceinline__ float lane_read(float v, int src) { return __int_as_float(__builtin_amdgcn_ds_bpermute(src << 2, __float_as_int(v))); }
; __device__ __forceinline__ void load_q_roped(const bf16_t* Qw, const float* __restrict__ wq, const float* __restrict__ RT, int pr, int pc, int hi, int lane, bf16x8 (&qr)[8]) {
;     ...
;   ss += lane_read(ss, lane ^ 32);
;   const float rstd = __builtin_amdgcn_rsqf(ss * (1.f / 128.f) + 1e-6f);
; #pragma unroll
;   for (int d0 = 0; d0 < 8; ++d0) { const f32x4 w0 = *(const f32x4*)(wq + d0 * 16), w1 = *(const f32x4*)(wq + d0 * 16 + 4);
; #pragma unroll
;     for (int e = 0; e < 8; ++e) y[d0][e] *= rstd * (e < 4 ? w0[e & 3] : w1[e & 3]); }
; #pragma unroll
;   for (int hf = 0; hf < 2; ++hf)
; #pragma unroll
;     for (int lo = 0; lo < 2; ++lo) { const int d0 = hf * 4 + lo;
;       const float* tp = RT + (size_t)((hf ? pc : pr) * 32 + lo * 16 + hi * 8) * 2;
;       f32x4 t[4];
; #pragma unroll
;       for (int q = 0; q < 4; ++q) t[q] = *(const f32x4*)(tp + 4 * q);
; #pragma unroll
;       for (int e = 0; e < 8; ++e) { const float cs = t[e >> 1][(e & 1) * 2], sn = t[e >> 1][(e & 1) * 2 + 1];
;         const float x1 = y[d0][e], x2 = y[d0 + 2][e]; y[d0][e] = x1 * cs - x2 * sn; y[d0 + 2][e] = x1 * sn + x2 * cs; } }
	v_add_f32_e32 v0, v235, v0
	v_pk_mul_f32 v[54:55], v[242:243], v[242:243]
	v_lshlrev_b32_e32 v248, 16, v79
	v_and_b32_e32 v249, 0xffff0000, v79
	v_add_f32_e32 v0, v54, v0
	v_add_f32_e32 v0, v55, v0
	v_pk_mul_f32 v[54:55], v[248:249], v[248:249]
	v_lshlrev_b32_e32 v206, 16, v80
	v_and_b32_e32 v207, 0xffff0000, v80
	v_add_f32_e32 v0, v54, v0
	v_add_f32_e32 v0, v55, v0
	v_pk_mul_f32 v[54:55], v[206:207], v[206:207]
	v_lshlrev_b32_e32 v204, 16, v81
	v_and_b32_e32 v205, 0xffff0000, v81
	v_add_f32_e32 v0, v54, v0
	v_add_f32_e32 v0, v55, v0
	v_pk_mul_f32 v[54:55], v[204:205], v[204:205]
	v_pk_mul_f32 v[52:53], v[200:201], v[200:201]
	v_add_f32_e32 v0, v54, v0
	v_add_f32_e32 v0, v55, v0
	v_add_f32_e32 v0, v52, v0
	v_pk_mul_f32 v[50:51], v[198:199], v[198:199]
	v_add_f32_e32 v0, v53, v0
	v_lshlrev_b32_e32 v240, 16, v56
	v_and_b32_e32 v241, 0xffff0000, v56
	v_add_f32_e32 v0, v50, v0
	v_lshlrev_b32_e32 v232, 16, v57
	v_and_b32_e32 v233, 0xffff0000, v57
	v_pk_mul_f32 v[56:57], v[240:241], v[240:241]
	v_add_f32_e32 v0, v51, v0
	v_add_f32_e32 v0, v56, v0
	v_pk_mul_f32 v[236:237], v[232:233], v[232:233]
	v_add_f32_e32 v0, v57, v0
	v_add_f32_e32 v0, v236, v0
	v_add_f32_e32 v0, v237, v0
	v_add_f32_e32 v0, v66, v0
	v_add_f32_e32 v0, v67, v0
	v_add_f32_e32 v0, v222, v0
	v_add_f32_e32 v0, v223, v0
	v_add_f32_e32 v0, v68, v0
	v_add_f32_e32 v0, v69, v0
	v_add_f32_e32 v0, v210, v0
	v_pk_mul_f32 v[168:169], v[142:143], v[142:143]
	v_add_f32_e32 v0, v211, v0
	v_lshlrev_b32_e32 v138, 16, v59
	v_and_b32_e32 v139, 0xffff0000, v59
	v_add_f32_e32 v0, v168, v0
	v_pk_mul_f32 v[148:149], v[138:139], v[138:139]
	v_add_f32_e32 v0, v169, v0
	v_lshlrev_b32_e32 v136, 16, v60
	v_and_b32_e32 v137, 0xffff0000, v60
	v_add_f32_e32 v0, v148, v0
	v_lshlrev_b32_e32 v140, 16, v63
	v_and_b32_e32 v141, 0xffff0000, v63
	v_lshlrev_b32_e32 v146, 16, v62
	v_and_b32_e32 v147, 0xffff0000, v62
	v_pk_mul_f32 v[62:63], v[136:137], v[136:137]
	v_add_f32_e32 v0, v149, v0
	v_lshlrev_b32_e32 v134, 16, v61
	v_and_b32_e32 v135, 0xffff0000, v61
	v_add_f32_e32 v0, v62, v0
	v_pk_mul_f32 v[58:59], v[134:135], v[134:135]
	v_add_f32_e32 v0, v63, v0
	v_lshlrev_b32_e32 v228, 16, v70
	v_and_b32_e32 v229, 0xffff0000, v70
	v_add_f32_e32 v0, v58, v0
	v_lshlrev_b32_e32 v220, 16, v71
	v_and_b32_e32 v221, 0xffff0000, v71
	v_pk_mul_f32 v[70:71], v[228:229], v[228:229]
	v_add_f32_e32 v0, v59, v0
	v_add_f32_e32 v0, v70, v0
	v_pk_mul_f32 v[224:225], v[220:221], v[220:221]
	v_add_f32_e32 v0, v71, v0
	v_lshlrev_b32_e32 v216, 16, v72
	v_and_b32_e32 v217, 0xffff0000, v72
	v_add_f32_e32 v0, v224, v0
	v_lshlrev_b32_e32 v192, 16, v73
	v_and_b32_e32 v193, 0xffff0000, v73
	v_pk_mul_f32 v[72:73], v[216:217], v[216:217]
	v_add_f32_e32 v0, v225, v0
	v_add_f32_e32 v0, v72, v0
	v_pk_mul_f32 v[212:213], v[192:193], v[192:193]
	v_add_f32_e32 v0, v73, v0
	v_add_f32_e32 v0, v212, v0
	v_pk_mul_f32 v[170:171], v[146:147], v[146:147]
	v_add_f32_e32 v0, v213, v0
	v_add_f32_e32 v0, v170, v0
	v_pk_mul_f32 v[160:161], v[140:141], v[140:141]
	v_add_f32_e32 v0, v171, v0
	v_lshlrev_b32_e32 v132, 16, v64
	v_and_b32_e32 v133, 0xffff0000, v64
	v_add_f32_e32 v0, v160, v0
	v_lshlrev_b32_e32 v130, 16, v65
	v_and_b32_e32 v131, 0xffff0000, v65
	v_pk_mul_f32 v[64:65], v[132:133], v[132:133]
	v_add_f32_e32 v0, v161, v0
	v_add_f32_e32 v0, v64, v0
	v_pk_mul_f32 v[60:61], v[130:131], v[130:131]
	v_add_f32_e32 v0, v65, v0
	v_add_f32_e32 v0, v60, v0
	v_add_f32_e32 v0, v61, v0
	ds_bpermute_b32 v50, v252, v0
	global_load_dwordx4 v[66:69], v195, s[48:49] offset:48
	global_load_dwordx4 v[70:73], v195, s[48:49] offset:32
	global_load_dwordx4 v[74:77], v195, s[48:49] offset:16
	global_load_dwordx4 v[78:81], v195, s[48:49]
	v_add_u32_e32 v168, 0, v176
	v_add_u32_e32 v169, 0, v177
	v_lshl_add_u64 v[170:171], s[40:41], 0, v[166:167]
	s_waitcnt lgkmcnt(0)
	v_add_f32_e32 v0, v0, v50
	v_mov_b32_e32 v50, 0x358637bd
	v_fmamk_f32 v0, v0, 0x3c000000, v50
	v_rsq_f32_e32 v0, v0
	global_load_dwordx4 v[50:53], v195, s[48:49] offset:176
	global_load_dwordx4 v[54:57], v195, s[48:49] offset:160
	global_load_dwordx4 v[58:61], v195, s[48:49] offset:144
	global_load_dwordx4 v[62:65], v195, s[48:49] offset:128
	v_pk_mul_f32 v[14:15], v[14:15], v[0:1] op_sel_hi:[1,0]
	v_pk_mul_f32 v[126:127], v[126:127], v[0:1] op_sel_hi:[1,0]
	v_pk_mul_f32 v[116:117], v[116:117], v[0:1] op_sel_hi:[1,0]
	v_pk_mul_f32 v[86:87], v[86:87], v[0:1] op_sel_hi:[1,0]
	v_pk_mul_f32 v[14:15], v[14:15], v[132:133]
	v_pk_mul_f32 v[132:133], v[126:127], v[146:147]
	v_pk_mul_f32 v[126:127], v[116:117], v[134:135]
	v_pk_mul_f32 v[114:115], v[114:115], v[0:1] op_sel_hi:[1,0]
	v_pk_mul_f32 v[112:113], v[112:113], v[0:1] op_sel_hi:[1,0]
	v_pk_mul_f32 v[90:91], v[90:91], v[0:1] op_sel_hi:[1,0]
	v_pk_mul_f32 v[116:117], v[86:87], v[242:243]
	v_lshl_add_u64 v[86:87], s[6:7], 0, v[166:167]
	v_pk_mul_f32 v[134:135], v[114:115], v[136:137]
	v_pk_mul_f32 v[136:137], v[112:113], v[138:139]
	v_pk_mul_f32 v[110:111], v[110:111], v[0:1] op_sel_hi:[1,0]
	v_pk_mul_f32 v[108:109], v[108:109], v[0:1] op_sel_hi:[1,0]
	v_pk_mul_f32 v[106:107], v[106:107], v[0:1] op_sel_hi:[1,0]
	v_pk_mul_f32 v[112:113], v[90:91], v[206:207]
	v_add_co_u32_e32 v90, vcc, s37, v86
	v_pk_mul_f32 v[138:139], v[110:111], v[142:143]
	v_pk_mul_f32 v[142:143], v[108:109], v[144:145]
	v_pk_mul_f32 v[144:145], v[106:107], v[214:215]
	v_pk_mul_f32 v[104:105], v[104:105], v[0:1] op_sel_hi:[1,0]
	v_pk_mul_f32 v[102:103], v[102:103], v[0:1] op_sel_hi:[1,0]
	v_pk_mul_f32 v[92:93], v[92:93], v[0:1] op_sel_hi:[1,0]
	v_pk_mul_f32 v[88:89], v[88:89], v[0:1] op_sel_hi:[1,0]
	v_addc_co_u32_e32 v91, vcc, 0, v87, vcc
	v_lshl_add_u64 v[106:107], s[8:9], 0, v[166:167]
; #define SLOAD(i, t) do { const long rb_ = TROW(t); const char* vt_ = (const char*)Vh + rb_ * (LDK * 2); const char* kt_ = (const char*)Kh + rb_ * (LDK * 2); \
;     sr_[i].vs0 = *(const bf16x8*)(vt_ + lo0); sr_[i].vs1 = *(const bf16x8*)(vt_ + lo0 + 32 * LDK * 2); \
;     sr_[i].ks0 = *(const bf16x8*)(kt_ + lo0); sr_[i].ks1 = *(const bf16x8*)(kt_ + lo0 + 32 * LDK * 2); } while (0)
; #define SWRITE(bb, i) do { *(bf16x8*)((char*)V_lds + (bb) * SHM_V + vst0) = sr_[i].vs0;          \
;     *(bf16x8*)((char*)V_lds + (bb) * SHM_V + vst1) = sr_[i].vs1; int kc = sc * 2;               \
;     *(bf16x8*)((char*)K_lds + (bb) * SHM_K + KSWZ(sr, kc)) = sr_[i].ks0;                       \
;     *(bf16x8*)((char*)K_lds + (bb) * SHM_K + KSWZ(32 + sr, kc)) = sr_[i].ks1; } while (0)
; __device__ __forceinline__ void load_q_roped(const bf16_t* Qw, const float* __restrict__ wq, const float* __restrict__ RT, int pr, int pc, int hi, int lane, bf16x8 (&qr)[8]) {
;     ...
;       for (int e = 0; e < 8; ++e) { const float cs = t[e >> 1][(e & 1) * 2], sn = t[e >> 1][(e & 1) * 2 + 1];
;         const float x1 = y[d0][e], x2 = y[d0 + 2][e]; y[d0][e] = x1 * cs - x2 * sn; y[d0 + 2][e] = x1 * sn + x2 * cs; } }
; template <bool META>
; __device__ __forceinline__ void attn_unit(const bf16_t* Q, bf16_t* Oo, const bf16_t* __restrict__ Kb, const bf16_t* __restrict__ Vb, int b, int kvh, int h, int qb, char* lds, const int tid, const float* qn, const float* RT) {
;     ...
;   f32x16 pA0, pA1, pB0, pB1; float mnA, mnB, alA, alB; bf16x8 pa0, pa1, pa2, pa3;
;   constexpr int SE = 0, SO = 0;
;   SLOAD(SE, 0); asm volatile("s_waitcnt vmcnt(0)" ::: "memory"); SWRITE(0, SE); __syncthreads();
	v_pk_mul_f32 v[146:147], v[104:105], v[218:219]
	v_pk_mul_f32 v[148:149], v[102:103], v[226:227]
	v_pk_mul_f32 v[110:111], v[92:93], v[204:205]
	v_pk_mul_f32 v[114:115], v[88:89], v[248:249]
	global_load_dwordx4 v[86:89], v[86:87], off
	s_nop 0
	global_load_dwordx4 v[90:93], v[90:91], off
	v_pk_mul_f32 v[128:129], v[128:129], v[0:1] op_sel_hi:[1,0]
	global_load_dwordx4 v[102:105], v[106:107], off
	v_add_co_u32_e32 v106, vcc, s37, v106
	v_pk_mul_f32 v[120:121], v[120:121], v[0:1] op_sel_hi:[1,0]
	s_nop 0
	v_addc_co_u32_e32 v107, vcc, 0, v107, vcc
	global_load_dwordx4 v[106:109], v[106:107], off
	v_pk_mul_f32 v[2:3], v[2:3], v[0:1] op_sel_hi:[1,0]
	v_pk_mul_f32 v[128:129], v[128:129], v[140:141]
	v_pk_mul_f32 v[140:141], v[120:121], v[220:221]
	v_pk_mul_f32 v[120:121], v[2:3], v[158:159]
	v_pk_mul_f32 v[2:3], v[16:17], v[0:1] op_sel_hi:[1,0]
	v_mov_b32_e32 v17, v48
	v_mov_b32_e32 v48, v47
	v_mov_b32_e32 v16, v46
	v_pk_mul_f32 v[46:47], v[48:49], v[116:117]
	v_pk_mul_f32 v[4:5], v[4:5], v[0:1] op_sel_hi:[1,0]
	v_pk_fma_f32 v[46:47], v[16:17], v[120:121], v[46:47] neg_lo:[0,0,1] neg_hi:[0,0,1]
	v_pk_mul_f32 v[16:17], v[16:17], v[116:117]
	v_pk_mul_f32 v[4:5], v[4:5], v[156:157]
	v_pk_fma_f32 v[16:17], v[48:49], v[120:121], v[16:17]
	v_mov_b32_e32 v49, v44
	v_mov_b32_e32 v44, v43
	v_mov_b32_e32 v48, v42
	v_pk_mul_f32 v[42:43], v[44:45], v[114:115]
	v_pk_mul_f32 v[6:7], v[6:7], v[0:1] op_sel_hi:[1,0]
	v_pk_fma_f32 v[42:43], v[48:49], v[4:5], v[42:43] neg_lo:[0,0,1] neg_hi:[0,0,1]
	v_pk_mul_f32 v[48:49], v[48:49], v[114:115]
	v_pk_mul_f32 v[6:7], v[6:7], v[154:155]
	v_pk_fma_f32 v[114:115], v[44:45], v[4:5], v[48:49]
	v_mov_b32_e32 v5, v40
	v_mov_b32_e32 v40, v39
	v_mov_b32_e32 v4, v38
	v_pk_mul_f32 v[38:39], v[40:41], v[112:113]
	v_pk_mul_f32 v[8:9], v[8:9], v[0:1] op_sel_hi:[1,0]
	v_pk_fma_f32 v[38:39], v[4:5], v[6:7], v[38:39] neg_lo:[0,0,1] neg_hi:[0,0,1]
	v_pk_mul_f32 v[4:5], v[4:5], v[112:113]
	v_pk_mul_f32 v[8:9], v[8:9], v[152:153]
	v_pk_fma_f32 v[112:113], v[40:41], v[6:7], v[4:5]
	v_mov_b32_e32 v5, v32
	v_mov_b32_e32 v32, v31
	v_mov_b32_e32 v4, v30
	v_pk_mul_f32 v[6:7], v[32:33], v[110:111]
	v_pk_mul_f32 v[94:95], v[94:95], v[0:1] op_sel_hi:[1,0]
	v_pk_fma_f32 v[30:31], v[4:5], v[8:9], v[6:7] neg_lo:[0,0,1] neg_hi:[0,0,1]
	v_pk_mul_f32 v[4:5], v[4:5], v[110:111]
	v_pk_mul_f32 v[94:95], v[94:95], v[200:201]
	v_pk_mul_f32 v[10:11], v[10:11], v[0:1] op_sel_hi:[1,0]
	v_pk_fma_f32 v[110:111], v[32:33], v[8:9], v[4:5]
	v_mov_b32_e32 v5, v36
	v_mov_b32_e32 v36, v35
	v_pk_mul_f32 v[10:11], v[10:11], v[150:151]
	v_mov_b32_e32 v4, v34
	v_pk_mul_f32 v[6:7], v[36:37], v[94:95]
	v_pk_mul_f32 v[96:97], v[96:97], v[0:1] op_sel_hi:[1,0]
	v_pk_fma_f32 v[116:117], v[4:5], v[10:11], v[6:7] neg_lo:[0,0,1] neg_hi:[0,0,1]
	v_pk_mul_f32 v[4:5], v[4:5], v[94:95]
	v_pk_mul_f32 v[96:97], v[96:97], v[198:199]
	v_pk_mul_f32 v[12:13], v[12:13], v[0:1] op_sel_hi:[1,0]
	v_pk_fma_f32 v[94:95], v[36:37], v[10:11], v[4:5]
	v_mov_b32_e32 v5, v28
	v_mov_b32_e32 v28, v27
	v_pk_mul_f32 v[12:13], v[12:13], v[202:203]
	v_mov_b32_e32 v4, v26
	v_pk_mul_f32 v[6:7], v[28:29], v[96:97]
	v_pk_mul_f32 v[98:99], v[98:99], v[0:1] op_sel_hi:[1,0]
	v_pk_fma_f32 v[120:121], v[4:5], v[12:13], v[6:7] neg_lo:[0,0,1] neg_hi:[0,0,1]
	v_pk_mul_f32 v[4:5], v[4:5], v[96:97]
	v_pk_mul_f32 v[98:99], v[98:99], v[240:241]
	v_pk_mul_f32 v[82:83], v[82:83], v[0:1] op_sel_hi:[1,0]
	v_pk_fma_f32 v[12:13], v[28:29], v[12:13], v[4:5]
	v_mov_b32_e32 v5, v24
	v_mov_b32_e32 v24, v23
	v_pk_mul_f32 v[82:83], v[82:83], v[238:239]
	v_mov_b32_e32 v4, v22
	v_pk_mul_f32 v[6:7], v[24:25], v[98:99]
	v_pk_mul_f32 v[100:101], v[100:101], v[0:1] op_sel_hi:[1,0]
	v_pk_fma_f32 v[96:97], v[4:5], v[82:83], v[6:7] neg_lo:[0,0,1] neg_hi:[0,0,1]
	v_pk_mul_f32 v[4:5], v[4:5], v[98:99]
	v_pk_mul_f32 v[124:125], v[124:125], v[0:1] op_sel_hi:[1,0]
	v_pk_mul_f32 v[122:123], v[122:123], v[0:1] op_sel_hi:[1,0]
	v_pk_mul_f32 v[118:119], v[118:119], v[0:1] op_sel_hi:[1,0]
	v_pk_mul_f32 v[100:101], v[100:101], v[232:233]
	v_pk_mul_f32 v[84:85], v[84:85], v[0:1] op_sel_hi:[1,0]
	v_pk_fma_f32 v[82:83], v[24:25], v[82:83], v[4:5]
	v_mov_b32_e32 v5, v20
	v_mov_b32_e32 v20, v19
	v_add_u32_e32 v0, 0, v179
	v_pk_mul_f32 v[84:85], v[84:85], v[230:231]
	v_mov_b32_e32 v4, v18
	v_pk_mul_f32 v[6:7], v[20:21], v[100:101]
	s_waitcnt vmcnt(0)
	s_waitcnt vmcnt(3)
	ds_write_b128 v168, v[86:89]
	s_waitcnt vmcnt(2)
	ds_write_b128 v169, v[90:93]
	s_waitcnt vmcnt(1)
	ds_write_b128 v0, v[102:105] offset:49152
	v_add_u32_e32 v0, 0, v180
	v_pk_mul_f32 v[2:3], v[2:3], v[130:131]
	v_pk_fma_f32 v[130:131], v[4:5], v[84:85], v[6:7] neg_lo:[0,0,1] neg_hi:[0,0,1]
	v_pk_mul_f32 v[4:5], v[4:5], v[100:101]
	s_waitcnt vmcnt(0)
	ds_write_b128 v0, v[106:109] offset:49152
	v_add_u32_e32 v0, 0, v182
	v_pk_fma_f32 v[84:85], v[20:21], v[84:85], v[4:5]
	s_waitcnt lgkmcnt(0)
	s_barrier
; __device__ __forceinline__ unsigned cvtpk(float lo, float hi) { const f32x2c v = {lo, hi}; const bf16x2c r = __builtin_convertvector(v, bf16x2c); return __builtin_bit_cast(unsigned, r); }
; __device__ __forceinline__ void qkt(f32x16& p0, f32x16& p1, const bf16_t* Ks, const bf16x8* qr, int r32, int hi) {
;   p0 = f32x16{}; p1 = f32x16{};
; #pragma unroll
;   for (int d0 = 0; d0 < 8; ++d0) { int cb = (d0 * 16 + hi * 8) * 2;
;     bf16x8 b0 = *reinterpret_cast<const bf16x8*>((const char*)Ks + KSWZ(r32, cb));
;     bf16x8 b1 = *reinterpret_cast<const bf16x8*>((const char*)Ks + KSWZ(32 + r32, cb));
;     p0 = __builtin_amdgcn_mfma_f32_32x32x16_bf16(b0, qr[d0], p0, 0, 0, 0);
;     p1 = __builtin_amdgcn_mfma_f32_32x32x16_bf16(b1, qr[d0], p1, 0, 0, 0); }
; }
; __device__ __forceinline__ void load_q_roped(const bf16_t* Qw, const float* __restrict__ wq, const float* __restrict__ RT, int pr, int pc, int hi, int lane, bf16x8 (&qr)[8]) {
;     ...
; #pragma unroll
;   for (int d0 = 0; d0 < 8; ++d0) { u32x4 w; w.x = cvtpk(y[d0][0], y[d0][1]); w.y = cvtpk(y[d0][2], y[d0][3]); w.z = cvtpk(y[d0][4], y[d0][5]); w.w = cvtpk(y[d0][6], y[d0][7]);
;     qr[d0] = *reinterpret_cast<bf16x8*>(&w); }
	ds_read_b128 v[4:7], v0 offset:49152
	v_pk_mul_f32 v[118:119], v[118:119], v[228:229]
	v_mov_b32_e32 v9, v80
	v_mov_b32_e32 v80, v79
	v_mov_b32_e32 v8, v78
	v_pk_mul_f32 v[10:11], v[80:81], v[118:119]
	v_cvt_pk_bf16_f32 v98, v46, v47
	v_cvt_pk_bf16_f32 v99, v42, v43
	v_cvt_pk_bf16_f32 v100, v38, v39
	v_cvt_pk_bf16_f32 v101, v30, v31
	v_mov_b32_e32 v89, v76
	v_mov_b32_e32 v76, v75
	v_pk_fma_f32 v[78:79], v[8:9], v[148:149], v[10:11] neg_lo:[0,0,1] neg_hi:[0,0,1]
	v_pk_mul_f32 v[86:87], v[8:9], v[118:119]
	ds_read_b128 v[8:11], v0 offset:57344
	s_waitcnt lgkmcnt(1)
	v_mfma_f32_32x32x16_bf16 v[18:33], v[4:7], v[98:101], 0
	v_mov_b32_e32 v88, v74
	v_mul_f32_e64 v4, v76, v140
	v_mul_f32_e64 v5, v77, v141
	v_add_u32_e32 v0, 0, v183
	v_fma_f32 v74, v88, v146, -v4
	v_fma_f32 v75, v89, v147, -v5
	ds_read_b128 v[4:7], v0 offset:49152
	v_pk_mul_f32 v[122:123], v[122:123], v[216:217]
	v_mov_b32_e32 v91, v72
	v_cvt_pk_bf16_f32 v102, v116, v117
	v_cvt_pk_bf16_f32 v103, v120, v121
	v_cvt_pk_bf16_f32 v104, v96, v97
	v_cvt_pk_bf16_f32 v105, v130, v131
	v_mov_b32_e32 v72, v71
	s_waitcnt lgkmcnt(1)
	v_mfma_f32_32x32x16_bf16 v[34:49], v[8:11], v[98:101], 0
	v_mov_b32_e32 v90, v70
	ds_read_b128 v[8:11], v0 offset:57344
	v_add_u32_e32 v0, 0, v184
	v_cvt_pk_bf16_f32 v106, v16, v17
	v_cvt_pk_bf16_f32 v107, v114, v115
	v_cvt_pk_bf16_f32 v108, v112, v113
	v_cvt_pk_bf16_f32 v109, v110, v111
	s_waitcnt lgkmcnt(1)
	v_mfma_f32_32x32x16_bf16 v[18:33], v[4:7], v[102:105], v[18:33]
	v_mul_f32_e64 v4, v72, v122
	v_mul_f32_e64 v5, v73, v123
	v_cvt_pk_bf16_f32 v110, v94, v95
	v_fma_f32 v70, v90, v144, -v4
	v_fma_f32 v71, v91, v145, -v5
	ds_read_b128 v[4:7], v0 offset:49152
	v_cvt_pk_bf16_f32 v111, v12, v13
	v_cvt_pk_bf16_f32 v112, v82, v83
	v_cvt_pk_bf16_f32 v113, v84, v85
	s_waitcnt lgkmcnt(1)
	v_mfma_f32_32x32x16_bf16 v[34:49], v[8:11], v[102:105], v[34:49]
	ds_read_b128 v[8:11], v0 offset:57344
	v_add_u32_e32 v0, 0, v185
	v_mov_b32_e32 v97, v60
	v_mov_b32_e32 v60, v59
	v_mov_b32_e32 v96, v58
	v_pk_mul_f32 v[124:125], v[124:125], v[192:193]
	v_mov_b32_e32 v93, v68
	s_waitcnt lgkmcnt(1)
	v_mfma_f32_32x32x16_bf16 v[18:33], v[4:7], v[106:109], v[18:33]
	ds_read_b128 v[4:7], v0 offset:49152
	v_mov_b32_e32 v68, v67
	v_mov_b32_e32 v92, v66
	v_mul_f32_e64 v66, v68, v124
	v_mul_f32_e64 v67, v69, v125
	v_mov_b32_e32 v59, v56
	v_pk_fma_f32 v[16:17], v[92:93], v[142:143], v[66:67] neg_lo:[0,0,1] neg_hi:[0,0,1]
	v_mov_b32_e32 v56, v55
	s_waitcnt lgkmcnt(1)
	v_mfma_f32_32x32x16_bf16 v[34:49], v[8:11], v[106:109], v[34:49]
	ds_read_b128 v[8:11], v0 offset:57344
	v_add_u32_e32 v0, 0, v186
	v_cvt_pk_bf16_f32 v114, v78, v79
	v_cvt_pk_bf16_f32 v115, v74, v75
	v_cvt_pk_bf16_f32 v116, v70, v71
	v_cvt_pk_bf16_f32 v117, v16, v17
	v_mov_b32_e32 v58, v54
	s_waitcnt lgkmcnt(1)
	v_mfma_f32_32x32x16_bf16 v[18:33], v[4:7], v[110:113], v[18:33]
	v_mul_f32_e64 v4, v60, v128
	v_mul_f32_e64 v5, v61, v129
	v_mov_b32_e32 v67, v64
	v_fma_f32 v12, v96, v136, -v4
	v_fma_f32 v13, v97, v137, -v5
	ds_read_b128 v[4:7], v0 offset:49152
	v_mov_b32_e32 v64, v63
	v_mov_b32_e32 v55, v52
	v_mov_b32_e32 v52, v51
	s_waitcnt lgkmcnt(1)
	v_mfma_f32_32x32x16_bf16 v[34:49], v[8:11], v[110:113], v[34:49]
	ds_read_b128 v[8:11], v0 offset:57344
	v_add_u32_e32 v0, 0, v187
	v_mov_b32_e32 v66, v62
	v_mul_f32_e64 v62, v64, v132
	v_mul_f32_e64 v63, v65, v133
	v_mov_b32_e32 v54, v50
	v_pk_fma_f32 v[62:63], v[66:67], v[138:139], v[62:63] neg_lo:[0,0,1] neg_hi:[0,0,1]
	v_cvt_pk_bf16_f32 v119, v12, v13
	s_waitcnt lgkmcnt(1)
	v_mfma_f32_32x32x16_bf16 v[18:33], v[4:7], v[114:117], v[18:33]
	v_mul_f32_e64 v4, v56, v14
	v_mul_f32_e64 v5, v57, v15
	v_cvt_pk_bf16_f32 v118, v62, v63
	v_fma_f32 v16, v58, v134, -v4
	v_fma_f32 v17, v59, v135, -v5
	ds_read_b128 v[4:7], v0 offset:49152
	v_cvt_pk_bf16_f32 v120, v16, v17
	v_pk_fma_f32 v[12:13], v[80:81], v[148:149], v[86:87]
	v_pk_mul_f32 v[14:15], v[58:59], v[14:15]
	s_waitcnt lgkmcnt(1)
	v_mfma_f32_32x32x16_bf16 v[34:49], v[8:11], v[114:117], v[34:49]
	v_mul_f32_e64 v8, v52, v2
	v_mul_f32_e64 v9, v53, v3
	v_mul_f32_e64 v2, v54, v2
	v_mul_f32_e64 v3, v55, v3
	v_fma_f32 v8, v54, v126, -v8
	v_fma_f32 v9, v55, v127, -v9
	v_pk_fma_f32 v[2:3], v[52:53], v[126:127], v[2:3]
	v_cvt_pk_bf16_f32 v121, v8, v9
	ds_read_b128 v[8:11], v0 offset:57344
	v_add_u32_e32 v0, 0, v188
	s_waitcnt lgkmcnt(1)
	v_mfma_f32_32x32x16_bf16 v[18:33], v[4:7], v[118:121], v[18:33]
	v_mul_f32_e64 v4, v88, v140
	v_mul_f32_e64 v5, v89, v141
	v_mov_b64_e32 v[248:249], v[174:175]
	v_fma_f32 v16, v76, v146, v4
	v_fma_f32 v17, v77, v147, v5
	v_pk_mul_f32 v[4:5], v[90:91], v[122:123]
	v_cvt_pk_bf16_f32 v122, v12, v13
	v_pk_fma_f32 v[50:51], v[72:73], v[144:145], v[4:5]
	ds_read_b128 v[4:7], v0 offset:49152
	s_waitcnt lgkmcnt(1)
	v_mfma_f32_32x32x16_bf16 v[34:49], v[8:11], v[118:121], v[34:49]
	v_mul_f32_e64 v8, v92, v124
	v_mul_f32_e64 v9, v93, v125
	v_cvt_pk_bf16_f32 v123, v16, v17
	v_fma_f32 v8, v68, v142, v8
	v_fma_f32 v9, v69, v143, v9
	v_cvt_pk_bf16_f32 v124, v50, v51
	v_cvt_pk_bf16_f32 v125, v8, v9
	ds_read_b128 v[8:11], v0 offset:57344
	v_add_u32_e32 v0, 0, v189
	s_waitcnt lgkmcnt(1)
	v_mfma_f32_32x32x16_bf16 v[18:33], v[4:7], v[122:125], v[18:33]
	v_mul_f32_e64 v4, v66, v132
	v_mul_f32_e64 v5, v67, v133
	v_mov_b64_e32 v[242:243], v[244:245]
	v_fma_f32 v12, v64, v138, v4
	v_fma_f32 v13, v65, v139, v5
	v_pk_mul_f32 v[4:5], v[96:97], v[128:129]
	v_cvt_pk_bf16_f32 v126, v12, v13
	v_pk_fma_f32 v[16:17], v[60:61], v[136:137], v[4:5]
	ds_read_b128 v[4:7], v0 offset:49152
	s_waitcnt lgkmcnt(1)
; #define SLOAD(i, t) do { const long rb_ = TROW(t); const char* vt_ = (const char*)Vh + rb_ * (LDK * 2); const char* kt_ = (const char*)Kh + rb_ * (LDK * 2); \
;     sr_[i].vs0 = *(const bf16x8*)(vt_ + lo0); sr_[i].vs1 = *(const bf16x8*)(vt_ + lo0 + 32 * LDK * 2); \
;     sr_[i].ks0 = *(const bf16x8*)(kt_ + lo0); sr_[i].ks1 = *(const bf16x8*)(kt_ + lo0 + 32 * LDK * 2); } while (0)
; #define SWRITE(bb, i) do { *(bf16x8*)((char*)V_lds + (bb) * SHM_V + vst0) = sr_[i].vs0;          \
;     *(bf16x8*)((char*)V_lds + (bb) * SHM_V + vst1) = sr_[i].vs1; int kc = sc * 2;               \
;     *(bf16x8*)((char*)K_lds + (bb) * SHM_K + KSWZ(sr, kc)) = sr_[i].ks0;                       \
;     *(bf16x8*)((char*)K_lds + (bb) * SHM_K + KSWZ(32 + sr, kc)) = sr_[i].ks1; } while (0)
; #define SWAIT() asm volatile("s_waitcnt vmcnt(0)" ::: "memory")
; __device__ __forceinline__ void partialSM(f32x16& p0, f32x16& p1, float& m_reg, float& mn, float& alpha) {
;   constexpr float C = ASCALE * 1.4426950408889634f;
;   float pmax = p0[0];
; #pragma unroll
;   for (int r = 1; r < 16; ++r) pmax = fmaxf(pmax, p0[r]);
; #pragma unroll
;   for (int r = 0; r < 16; ++r) pmax = fmaxf(pmax, p1[r]);
;   { auto rr = __builtin_amdgcn_permlane32_swap(__float_as_uint(pmax), __float_as_uint(pmax), false, false);
;     pmax = fmaxf(__uint_as_float(rr[0]), __uint_as_float(rr[1])); }
;   if (__builtin_expect(__all(pmax - m_reg <= ATHR / ASCALE), 1)) { mn = m_reg; alpha = 1.f; }
;   else { mn = fmaxf(m_reg, pmax); alpha = __builtin_amdgcn_exp2f((m_reg - mn) * C); m_reg = mn; }
;   float mnC = -mn * C;
; #pragma unroll
;   for (int r = 0; r < 16; ++r) p0[r] = fmaf(p0[r], C, mnC);
; #pragma unroll
;   for (int r = 0; r < 16; ++r) p1[r] = fmaf(p1[r], C, mnC);
; #pragma unroll
;   for (int r = 0; r < 16; ++r) p0[r] = __builtin_amdgcn_exp2f(p0[r]);
; }
; template <bool META>
; __device__ __forceinline__ void attn_unit(const bf16_t* Q, bf16_t* Oo, const bf16_t* __restrict__ Kb, const bf16_t* __restrict__ Vb, int b, int kvh, int h, int qb, char* lds, const int tid, const float* qn, const float* RT) {
;     ...
;   SLOAD(SE, 0); asm volatile("s_waitcnt vmcnt(0)" ::: "memory"); SWRITE(0, SE); __syncthreads();
;   qkt(pA0, pA1, K_lds, qr, r32, hi); partialSM(pA0, pA1, m_reg, mnA, alA);
;   SLOAD(SO, 1);
;   SWAIT(); SWRITE(1, SO); __syncthreads();
	v_mfma_f32_32x32x16_bf16 v[34:49], v[8:11], v[122:125], v[34:49]
	v_fma_f32 v8, v56, v134, v14
	v_fma_f32 v9, v57, v135, v15
	v_cvt_pk_bf16_f32 v127, v16, v17
	v_cvt_pk_bf16_f32 v128, v8, v9
	v_cvt_pk_bf16_f32 v129, v2, v3
	ds_read_b128 v[8:11], v0 offset:57344
	v_mov_b32_e32 v245, v196
	s_waitcnt lgkmcnt(1)
	v_mfma_f32_32x32x16_bf16 v[18:33], v[4:7], v[126:129], v[18:33]
	s_waitcnt lgkmcnt(0)
	v_mfma_f32_32x32x16_bf16 v[34:49], v[8:11], v[126:129], v[34:49]
	s_nop 9
	v_max_f32_e32 v0, v19, v19
	v_max_f32_e32 v2, v18, v18
	v_max_f32_e32 v0, v2, v0
	v_max3_f32 v0, v0, v20, v21
	v_max3_f32 v0, v0, v22, v23
	v_max3_f32 v0, v0, v24, v25
	v_max3_f32 v0, v0, v26, v27
	v_max3_f32 v0, v0, v28, v29
	v_max3_f32 v0, v0, v30, v31
	v_max3_f32 v0, v0, v32, v33
	v_max3_f32 v0, v0, v34, v35
	v_max3_f32 v0, v0, v36, v37
	v_max3_f32 v0, v0, v38, v39
	v_max3_f32 v0, v0, v40, v41
	v_max3_f32 v0, v0, v42, v43
	v_max3_f32 v0, v0, v44, v45
	v_max3_f32 v0, v0, v46, v47
	v_max3_f32 v0, v0, v48, v49
	v_mov_b32_e32 v2, v0
	s_nop 1
	v_permlane32_swap_b32_e32 v0, v2
	v_max_f32_e32 v2, v2, v2
	v_max_f32_e32 v0, v0, v0
	v_max_f32_e32 v0, v0, v2
	v_add_f32_e32 v2, 0x7149f2ca, v0
	v_cmp_ge_f32_e32 vcc, s25, v2
	s_cmp_eq_u64 vcc, exec
	s_cselect_b64 vcc, -1, 0
	s_bitset1_b32 s0, 15
	s_add_u32 s6, s42, s0
	s_addc_u32 s7, s43, s1
	s_add_u32 s8, s40, s0
	v_lshl_add_u64 v[2:3], s[6:7], 0, v[166:167]
	s_addc_u32 s9, s41, s1
	v_add_co_u32_e64 v4, s[0:1], s37, v2
	v_max_f32_e32 v0, 0xf149f2ca, v0
	s_nop 0
	v_addc_co_u32_e64 v5, s[0:1], 0, v3, s[0:1]
	global_load_dwordx4 v[50:53], v[2:3], off
	global_load_dwordx4 v[54:57], v[4:5], off
	v_lshl_add_u64 v[2:3], s[8:9], 0, v[166:167]
	global_load_dwordx4 v[58:61], v[2:3], off
	v_add_co_u32_e64 v2, s[0:1], s37, v2
	v_cndmask_b32_e32 v150, v0, v246, vcc
	s_nop 0
	v_addc_co_u32_e64 v3, s[0:1], 0, v3, s[0:1]
	global_load_dwordx4 v[62:65], v[2:3], off
	v_sub_f32_e32 v2, 0xf149f2ca, v0
	v_mul_f32_e32 v2, 0x3e0293ee, v2
	v_exp_f32_e32 v66, v2
	v_mul_f32_e32 v0, 0xbe0293ee, v150
	v_fmamk_f32 v18, v18, 0x3e0293ee, v0
	v_fmamk_f32 v19, v19, 0x3e0293ee, v0
	v_cndmask_b32_e64 v192, v66, 1.0, vcc
	v_mov_b32_e32 v66, v0
	v_fmamk_f32 v20, v20, 0x3e0293ee, v0
	v_fmamk_f32 v21, v21, 0x3e0293ee, v0
	v_fmamk_f32 v22, v22, 0x3e0293ee, v0
	v_fmamk_f32 v23, v23, 0x3e0293ee, v0
	v_fmamk_f32 v24, v24, 0x3e0293ee, v0
	v_fmamk_f32 v25, v25, 0x3e0293ee, v0
	v_fmamk_f32 v26, v26, 0x3e0293ee, v0
	v_fmamk_f32 v27, v27, 0x3e0293ee, v0
	v_fmamk_f32 v28, v28, 0x3e0293ee, v0
	v_fmamk_f32 v29, v29, 0x3e0293ee, v0
	v_fmamk_f32 v30, v30, 0x3e0293ee, v0
	v_fmamk_f32 v31, v31, 0x3e0293ee, v0
	v_fmamk_f32 v32, v32, 0x3e0293ee, v0
	v_fmac_f32_e32 v66, 0x3e0293ee, v33
	s_add_i32 s0, 0, 0x10000
	s_mov_b32 s6, s5
	s_mov_b32 s7, s5
	s_mov_b32 s8, s5
	s_mov_b32 s9, s5
	v_mov_b64_e32 v[2:3], s[4:5]
	v_pk_fma_f32 v[130:131], v[48:49], s[36:37], v[0:1] op_sel_hi:[1,0,0]
	v_pk_fma_f32 v[132:133], v[46:47], s[36:37], v[0:1] op_sel_hi:[1,0,0]
	v_pk_fma_f32 v[134:135], v[44:45], s[36:37], v[0:1] op_sel_hi:[1,0,0]
	v_pk_fma_f32 v[136:137], v[42:43], s[36:37], v[0:1] op_sel_hi:[1,0,0]
	v_pk_fma_f32 v[138:139], v[40:41], s[36:37], v[0:1] op_sel_hi:[1,0,0]
	v_pk_fma_f32 v[140:141], v[38:39], s[36:37], v[0:1] op_sel_hi:[1,0,0]
	v_pk_fma_f32 v[142:143], v[36:37], s[36:37], v[0:1] op_sel_hi:[1,0,0]
	v_pk_fma_f32 v[144:145], v[34:35], s[36:37], v[0:1] op_sel_hi:[1,0,0]
	v_exp_f32_e32 v146, v18
	v_exp_f32_e32 v147, v19
	v_exp_f32_e32 v148, v20
	v_exp_f32_e32 v159, v21
	v_exp_f32_e32 v160, v22
	v_exp_f32_e32 v209, v23
	v_exp_f32_e32 v149, v24
	v_exp_f32_e32 v161, v25
	v_exp_f32_e32 v151, v26
	v_exp_f32_e32 v153, v27
	v_exp_f32_e32 v154, v28
	v_exp_f32_e32 v157, v29
	v_exp_f32_e32 v152, v30
	v_exp_f32_e32 v155, v31
	v_exp_f32_e32 v156, v32
	v_exp_f32_e32 v158, v66
	v_add_u32_e32 v0, s0, v179
	v_mov_b64_e32 v[16:17], s[18:19]
	s_waitcnt vmcnt(0)
	s_waitcnt vmcnt(3)
	ds_write_b128 v168, v[50:53] offset:16384
	s_waitcnt vmcnt(2)
	ds_write_b128 v169, v[54:57] offset:16384
	v_mov_b64_e32 v[4:5], s[6:7]
	s_waitcnt vmcnt(1)
	ds_write_b128 v0, v[58:61]
	v_add_u32_e32 v0, s0, v180
	v_mov_b64_e32 v[6:7], s[8:9]
	v_mov_b64_e32 v[8:9], s[10:11]
	v_mov_b64_e32 v[10:11], s[12:13]
	v_mov_b64_e32 v[12:13], s[14:15]
	v_mov_b64_e32 v[14:15], s[16:17]
	s_waitcnt vmcnt(0)
	ds_write_b128 v0, v[62:65]
	v_mov_b64_e32 v[64:65], v[16:17]
	v_mov_b64_e32 v[48:49], v[16:17]
	v_mov_b64_e32 v[32:33], v[16:17]
	v_lshl_add_u64 v[168:169], s[42:43], 0, v[166:167]
	s_mov_b64 s[12:13], s[42:43]
	s_mov_b64 s[14:15], s[40:41]
	v_add_u32_e32 v238, 0x4000, v166
	s_bitset1_b32 s90, 7
	v_mov_b32_e32 v0, 0
	s_mov_b32 s4, -1
	v_mov_b64_e32 v[62:63], v[14:15]
	v_mov_b64_e32 v[60:61], v[12:13]
	v_mov_b64_e32 v[58:59], v[10:11]
	v_mov_b64_e32 v[56:57], v[8:9]
	v_mov_b64_e32 v[54:55], v[6:7]
	v_mov_b64_e32 v[52:53], v[4:5]
	v_mov_b64_e32 v[50:51], v[2:3]
	v_mov_b64_e32 v[46:47], v[14:15]
	v_mov_b64_e32 v[44:45], v[12:13]
	v_mov_b64_e32 v[42:43], v[10:11]
	v_mov_b64_e32 v[40:41], v[8:9]
	v_mov_b64_e32 v[38:39], v[6:7]
	v_mov_b64_e32 v[36:37], v[4:5]
	v_mov_b64_e32 v[34:35], v[2:3]
	v_mov_b64_e32 v[30:31], v[14:15]
	v_mov_b64_e32 v[28:29], v[12:13]
	v_mov_b64_e32 v[26:27], v[10:11]
	v_mov_b64_e32 v[24:25], v[8:9]
	v_mov_b64_e32 v[22:23], v[6:7]
	v_mov_b64_e32 v[20:21], v[4:5]
	v_mov_b64_e32 v[18:19], v[2:3]
	s_waitcnt lgkmcnt(0)
	s_barrier
; #define SBAR() __builtin_amdgcn_sched_barrier(0)
; #define SLOAD(i, t) do { const long rb_ = TROW(t); const char* vt_ = (const char*)Vh + rb_ * (LDK * 2); const char* kt_ = (const char*)Kh + rb_ * (LDK * 2); \
;     sr_[i].vs0 = *(const bf16x8*)(vt_ + lo0); sr_[i].vs1 = *(const bf16x8*)(vt_ + lo0 + 32 * LDK * 2); \
;     sr_[i].ks0 = *(const bf16x8*)(kt_ + lo0); sr_[i].ks1 = *(const bf16x8*)(kt_ + lo0 + 32 * LDK * 2); } while (0)
; __device__ __forceinline__ void finishSM(f32x16& p0, f32x16& p1, float alpha, float& l_reg, bf16x8& pa0, bf16x8& pa1, bf16x8& pa2, bf16x8& pa3) {
; #pragma unroll
;   for (int r = 0; r < 16; ++r) p1[r] = __builtin_amdgcn_exp2f(p1[r]);
;   float ps = 0;
; #pragma unroll
;   for (int r = 0; r < 16; ++r) ps += p0[r];
; #pragma unroll
;   for (int r = 0; r < 16; ++r) ps += p1[r];
;   { auto rr = __builtin_amdgcn_permlane32_swap(__float_as_uint(ps), __float_as_uint(ps), false, false);
;     ps = __uint_as_float(rr[0]) + __uint_as_float(rr[1]); }
;   l_reg = l_reg * alpha + ps;
;     ...
;   PK4(p0, 0, pa0); PK4(p0, 8, pa1); PK4(p1, 0, pa2); PK4(p1, 8, pa3);
; template <bool META>
; __device__ __forceinline__ void attn_unit(const bf16_t* Q, bf16_t* Oo, const bf16_t* __restrict__ Kb, const bf16_t* __restrict__ Vb, int b, int kvh, int h, int qb, char* lds, const int tid, const float* qn, const float* RT) {
;     ...
;   for (int j = 1; j + 1 < NT; j += 2) {
;     const int bn = bc == 2 ? 0 : bc + 1, bp = bc == 0 ? 2 : bc - 1;
;     SBAR(); qkt(pB0, pB1, (bf16_t*)((char*)K_lds + bc * SHM_K), qr, r32, hi);
;     finishSM(pA0, pA1, alA, l_reg, pa0, pa1, pa2, pa3); SBAR();
;     SLOAD(SO, j + 1);
;     SBAR();
;     pv_d0(o, vb0 + bp * (int)SHM_V, pa0, pa1, pa2, pa3); partialSM(pB0, pB1, m_reg, mnB, alB);
.LBB0_260:
	s_mov_b32 s6, s28
	v_sub_co_u32_e64 v66, s[0:1], s6, 1
	s_and_b64 s[0:1], s[0:1], exec
	v_readfirstlane_b32 s0, v66
	s_cselect_b32 s28, 2, s0
	s_lshl_b32 s9, s6, 14
	s_add_i32 s0, s9, 0
	v_add_u32_e32 v70, s0, v182
	ds_read_b128 v[66:69], v70 offset:49152
	ds_read_b128 v[70:73], v70 offset:57344
	v_add_u32_e32 v193, s0, v183
	ds_read_b128 v[210:213], v193 offset:49152
	ds_read_b128 v[214:217], v193 offset:57344
	v_add_u32_e32 v193, s0, v184
	s_waitcnt lgkmcnt(3)
	v_mfma_f32_32x32x16_bf16 v[82:97], v[66:69], v[98:101], 0
	v_exp_f32_e32 v144, v144
	v_exp_f32_e32 v145, v145
	v_exp_f32_e32 v142, v142
	v_exp_f32_e32 v143, v143
	v_exp_f32_e32 v140, v140
	v_exp_f32_e32 v141, v141
	v_exp_f32_e32 v138, v138
	s_waitcnt lgkmcnt(2)
	v_mfma_f32_32x32x16_bf16 v[66:81], v[70:73], v[98:101], 0
	v_exp_f32_e32 v139, v139
	v_exp_f32_e32 v136, v136
	v_exp_f32_e32 v137, v137
	v_exp_f32_e32 v134, v134
	v_exp_f32_e32 v135, v135
	v_exp_f32_e32 v132, v132
	v_exp_f32_e32 v133, v133
	s_waitcnt lgkmcnt(1)
	v_mfma_f32_32x32x16_bf16 v[82:97], v[210:213], v[102:105], v[82:97]
	v_exp_f32_e32 v130, v130
	v_exp_f32_e32 v131, v131
	s_waitcnt lgkmcnt(0)
	v_mfma_f32_32x32x16_bf16 v[66:81], v[214:217], v[102:105], v[66:81]
	ds_read_b128 v[210:213], v193 offset:49152
	ds_read_b128 v[214:217], v193 offset:57344
	v_add_u32_e32 v193, s0, v185
	s_waitcnt lgkmcnt(1)
	v_mfma_f32_32x32x16_bf16 v[82:97], v[210:213], v[106:109], v[82:97]
	s_waitcnt lgkmcnt(0)
	v_mfma_f32_32x32x16_bf16 v[66:81], v[214:217], v[106:109], v[66:81]
	ds_read_b128 v[210:213], v193 offset:49152
	ds_read_b128 v[214:217], v193 offset:57344
	v_add_u32_e32 v193, s0, v186
	s_waitcnt lgkmcnt(1)
	v_mfma_f32_32x32x16_bf16 v[82:97], v[210:213], v[110:113], v[82:97]
	s_waitcnt lgkmcnt(0)
	v_mfma_f32_32x32x16_bf16 v[66:81], v[214:217], v[110:113], v[66:81]
	ds_read_b128 v[210:213], v193 offset:49152
	ds_read_b128 v[214:217], v193 offset:57344
	v_add_u32_e32 v193, s0, v187
	s_waitcnt lgkmcnt(1)
	v_mfma_f32_32x32x16_bf16 v[82:97], v[210:213], v[114:117], v[82:97]
	s_waitcnt lgkmcnt(0)
	v_mfma_f32_32x32x16_bf16 v[66:81], v[214:217], v[114:117], v[66:81]
	ds_read_b128 v[210:213], v193 offset:49152
	ds_read_b128 v[214:217], v193 offset:57344
	v_add_u32_e32 v193, s0, v188
	s_waitcnt lgkmcnt(1)
	v_mfma_f32_32x32x16_bf16 v[82:97], v[210:213], v[118:121], v[82:97]
	s_waitcnt lgkmcnt(0)
	v_mfma_f32_32x32x16_bf16 v[66:81], v[214:217], v[118:121], v[66:81]
	ds_read_b128 v[210:213], v193 offset:49152
	ds_read_b128 v[214:217], v193 offset:57344
	v_add_u32_e32 v193, s0, v189
	s_waitcnt lgkmcnt(1)
	v_mfma_f32_32x32x16_bf16 v[82:97], v[210:213], v[122:125], v[82:97]
	s_waitcnt lgkmcnt(0)
	v_mfma_f32_32x32x16_bf16 v[66:81], v[214:217], v[122:125], v[66:81]
	ds_read_b128 v[210:213], v193 offset:49152
	ds_read_b128 v[214:217], v193 offset:57344
	v_add_f32_e32 v193, v147, v146
	v_add_f32_e32 v193, v148, v193
	v_add_f32_e32 v193, v159, v193
	v_add_f32_e32 v193, v160, v193
	v_add_f32_e32 v193, v209, v193
	v_add_f32_e32 v193, v149, v193
	v_add_f32_e32 v193, v161, v193
	v_add_f32_e32 v193, v151, v193
	v_add_f32_e32 v193, v153, v193
	v_add_f32_e32 v193, v154, v193
	v_add_f32_e32 v193, v157, v193
	v_add_f32_e32 v193, v152, v193
	v_add_f32_e32 v193, v155, v193
	v_add_f32_e32 v193, v156, v193
	v_add_f32_e32 v193, v158, v193
	v_add_f32_e32 v193, v144, v193
	v_add_f32_e32 v193, v145, v193
	v_add_f32_e32 v193, v142, v193
	v_add_f32_e32 v193, v143, v193
	v_add_f32_e32 v193, v140, v193
	v_add_f32_e32 v193, v141, v193
	v_add_f32_e32 v193, v138, v193
	v_add_f32_e32 v193, v139, v193
	v_add_f32_e32 v193, v136, v193
	v_add_f32_e32 v193, v137, v193
	s_waitcnt lgkmcnt(1)
	v_mfma_f32_32x32x16_bf16 v[82:97], v[210:213], v[126:129], v[82:97]
	v_add_f32_e32 v193, v134, v193
	v_add_f32_e32 v193, v135, v193
	v_add_f32_e32 v193, v132, v193
	v_add_f32_e32 v193, v133, v193
	v_add_f32_e32 v193, v130, v193
	v_add_f32_e32 v193, v131, v193
	v_mov_b32_e32 v195, v193
	s_waitcnt lgkmcnt(0)
	v_mfma_f32_32x32x16_bf16 v[66:81], v[214:217], v[126:129], v[66:81]
	v_cvt_pk_bf16_f32 v146, v146, v147
	v_cvt_pk_bf16_f32 v147, v148, v159
	v_cvt_pk_bf16_f32 v148, v160, v209
	v_permlane32_swap_b32_e32 v193, v195
	v_cvt_pk_bf16_f32 v149, v149, v161
	v_permlane32_swap_b32_e32 v146, v148
	v_cvt_pk_bf16_f32 v210, v151, v153
	v_cvt_pk_bf16_f32 v211, v154, v157
	v_cvt_pk_bf16_f32 v212, v152, v155
	v_cvt_pk_bf16_f32 v213, v156, v158
	v_cvt_pk_bf16_f32 v152, v144, v145
	v_cvt_pk_bf16_f32 v153, v142, v143
	v_cvt_pk_bf16_f32 v154, v140, v141
	v_cvt_pk_bf16_f32 v155, v138, v139
	v_cvt_pk_bf16_f32 v156, v136, v137
	v_cvt_pk_bf16_f32 v157, v134, v135
	v_cvt_pk_bf16_f32 v158, v132, v133
	v_cvt_pk_bf16_f32 v159, v130, v131
	v_permlane32_swap_b32_e32 v147, v149
	v_permlane32_swap_b32_e32 v210, v212
	v_permlane32_swap_b32_e32 v211, v213
	v_permlane32_swap_b32_e32 v152, v154
	v_permlane32_swap_b32_e32 v153, v155
	v_permlane32_swap_b32_e32 v156, v158
	v_permlane32_swap_b32_e32 v157, v159
	s_cmpk_lg_i32 s4, 0xfd
	s_cselect_b64 s[0:1], -1, 0
	s_cmpk_eq_i32 s4, 0xfd
	s_cselect_b64 s[40:41], -1, 0
	s_and_b64 s[10:11], s[40:41], exec
	s_cselect_b32 s11, s44, s91
	s_cselect_b32 s10, s31, s90
	s_lshl_b64 s[10:11], s[10:11], 9
	s_add_u32 s16, s12, s10
	s_addc_u32 s17, s13, s11
	s_add_u32 s18, s14, s10
	s_addc_u32 s19, s15, s11
	global_load_dwordx4 v[130:133], v166, s[16:17]
	global_load_dwordx4 v[134:137], v238, s[16:17]
	global_load_dwordx4 v[138:141], v166, s[18:19]
	global_load_dwordx4 v[142:145], v238, s[18:19]
	s_lshl_b32 s8, s28, 14
	v_add_u32_e32 v151, s8, v178
	ds_read_b64_tr_b16 v[214:215], v151 offset:0
	ds_read_b64_tr_b16 v[216:217], v151 offset:0x800
	ds_read_b64_tr_b16 v[218:219], v151 offset:0x1000
	ds_read_b64_tr_b16 v[220:221], v151 offset:0x1800
	ds_read_b64_tr_b16 v[222:223], v151 offset:0x2000
	ds_read_b64_tr_b16 v[224:225], v151 offset:0x2800
	ds_read_b64_tr_b16 v[226:227], v151 offset:0x3000
	ds_read_b64_tr_b16 v[228:229], v151 offset:0x3800
	s_waitcnt lgkmcnt(6)
; #define SBAR() __builtin_amdgcn_sched_barrier(0)
; #define SWRITE(bb, i) do { *(bf16x8*)((char*)V_lds + (bb) * SHM_V + vst0) = sr_[i].vs0;          \
;     *(bf16x8*)((char*)V_lds + (bb) * SHM_V + vst1) = sr_[i].vs1; int kc = sc * 2;               \
;     *(bf16x8*)((char*)K_lds + (bb) * SHM_K + KSWZ(sr, kc)) = sr_[i].ks0;                       \
;     *(bf16x8*)((char*)K_lds + (bb) * SHM_K + KSWZ(32 + sr, kc)) = sr_[i].ks1; } while (0)
; #define SWAIT() asm volatile("s_waitcnt vmcnt(0)" ::: "memory")
; #define RESC(a) do { if (__any((a) < 1.f)) { if (hi == 0) al_l[r32] = (a); asm volatile("s_waitcnt lgkmcnt(0)" ::: "memory"); \
;     _Pragma("unroll") for (int d = 0; d < 4; ++d) _Pragma("unroll") for (int r = 0; r < 16; ++r) o[d][r] *= al_l[crow(r, hi)]; } } while (0)
; template <int D0> __device__ __forceinline__ void pv_one(f32x16& od, int vb, bf16x8 pa0, bf16x8 pa1, bf16x8 pa2, bf16x8 pa3) {
;   const s16x4 l0 = tr_read<v_rd_off(D0, 0, 0)>(vb), h0 = tr_read<v_rd_off(D0, 0, 1)>(vb), l1 = tr_read<v_rd_off(D0, 1, 0)>(vb), h1 = tr_read<v_rd_off(D0, 1, 1)>(vb);
;   const s16x4 l2 = tr_read<v_rd_off(D0, 2, 0)>(vb), h2 = tr_read<v_rd_off(D0, 2, 1)>(vb), l3 = tr_read<v_rd_off(D0, 3, 0)>(vb), h3 = tr_read<v_rd_off(D0, 3, 1)>(vb);
;   asm volatile("s_waitcnt lgkmcnt(0)" ::: "memory"); SBAR();
;     ...
;   od = __builtin_amdgcn_mfma_f32_32x32x16_bf16(pa0, PK(l0, h0), od, 0, 0, 0);
;   od = __builtin_amdgcn_mfma_f32_32x32x16_bf16(pa1, PK(l1, h1), od, 0, 0, 0);
;   od = __builtin_amdgcn_mfma_f32_32x32x16_bf16(pa2, PK(l2, h2), od, 0, 0, 0);
;   od = __builtin_amdgcn_mfma_f32_32x32x16_bf16(pa3, PK(l3, h3), od, 0, 0, 0);
;     ...
; }
; __device__ __forceinline__ void pv_d0(f32x16* o, int vb, bf16x8 pa0, bf16x8 pa1, bf16x8 pa2, bf16x8 pa3) {
;   pv_one<0>(o[0], vb, pa0, pa1, pa2, pa3); pv_one<1>(o[1], vb, pa0, pa1, pa2, pa3); pv_one<2>(o[2], vb, pa0, pa1, pa2, pa3); pv_one<3>(o[3], vb, pa0, pa1, pa2, pa3);
; template <bool META>
; __device__ __forceinline__ void attn_unit(const bf16_t* Q, bf16_t* Oo, const bf16_t* __restrict__ Kb, const bf16_t* __restrict__ Vb, int b, int kvh, int h, int qb, char* lds, const int tid, const float* qn, const float* RT) {
;     ...
;     pv_d0(o, vb0 + bp * (int)SHM_V, pa0, pa1, pa2, pa3); partialSM(pB0, pB1, m_reg, mnB, alB);
;     SWAIT(); SWRITE(bn, SE);
;     RESC(alB); __syncthreads();
	s_nop 0
	v_mfma_f32_32x32x16_bf16 v[2:17], v[146:149], v[214:217], v[2:17]
	ds_read_b64_tr_b16 v[214:215], v151 offset:0x200
	ds_read_b64_tr_b16 v[216:217], v151 offset:0xa00
	s_waitcnt lgkmcnt(6)
	v_mfma_f32_32x32x16_bf16 v[2:17], v[210:213], v[218:221], v[2:17]
	ds_read_b64_tr_b16 v[218:219], v151 offset:0x1200
	ds_read_b64_tr_b16 v[220:221], v151 offset:0x1a00
	s_waitcnt lgkmcnt(6)
	v_mfma_f32_32x32x16_bf16 v[2:17], v[152:155], v[222:225], v[2:17]
	ds_read_b64_tr_b16 v[222:223], v151 offset:0x2200
	ds_read_b64_tr_b16 v[224:225], v151 offset:0x2a00
	s_waitcnt lgkmcnt(6)
	v_mfma_f32_32x32x16_bf16 v[2:17], v[156:159], v[226:229], v[2:17]
	ds_read_b64_tr_b16 v[226:227], v151 offset:0x3200
	ds_read_b64_tr_b16 v[228:229], v151 offset:0x3a00
	s_waitcnt lgkmcnt(6)
	v_mfma_f32_32x32x16_bf16 v[50:65], v[146:149], v[214:217], v[50:65]
	ds_read_b64_tr_b16 v[214:215], v151 offset:0x400
	ds_read_b64_tr_b16 v[216:217], v151 offset:0xc00
	s_waitcnt lgkmcnt(6)
	v_mfma_f32_32x32x16_bf16 v[50:65], v[210:213], v[218:221], v[50:65]
	ds_read_b64_tr_b16 v[218:219], v151 offset:0x1400
	ds_read_b64_tr_b16 v[220:221], v151 offset:0x1c00
	s_waitcnt lgkmcnt(6)
	v_mfma_f32_32x32x16_bf16 v[50:65], v[152:155], v[222:225], v[50:65]
	ds_read_b64_tr_b16 v[222:223], v151 offset:0x2400
	ds_read_b64_tr_b16 v[224:225], v151 offset:0x2c00
	s_waitcnt lgkmcnt(6)
	v_mfma_f32_32x32x16_bf16 v[50:65], v[156:159], v[226:229], v[50:65]
	ds_read_b64_tr_b16 v[226:227], v151 offset:0x3400
	ds_read_b64_tr_b16 v[228:229], v151 offset:0x3c00
	s_waitcnt lgkmcnt(6)
	v_mfma_f32_32x32x16_bf16 v[34:49], v[146:149], v[214:217], v[34:49]
	ds_read_b64_tr_b16 v[214:215], v151 offset:0x600
	ds_read_b64_tr_b16 v[216:217], v151 offset:0xe00
	s_waitcnt lgkmcnt(6)
	v_mfma_f32_32x32x16_bf16 v[34:49], v[210:213], v[218:221], v[34:49]
	ds_read_b64_tr_b16 v[218:219], v151 offset:0x1600
	ds_read_b64_tr_b16 v[220:221], v151 offset:0x1e00
	s_waitcnt lgkmcnt(6)
	v_mfma_f32_32x32x16_bf16 v[34:49], v[152:155], v[222:225], v[34:49]
	ds_read_b64_tr_b16 v[222:223], v151 offset:0x2600
	ds_read_b64_tr_b16 v[224:225], v151 offset:0x2e00
	s_waitcnt lgkmcnt(6)
	v_mfma_f32_32x32x16_bf16 v[34:49], v[156:159], v[226:229], v[34:49]
	ds_read_b64_tr_b16 v[226:227], v151 offset:0x3600
	ds_read_b64_tr_b16 v[228:229], v151 offset:0x3e00
	s_waitcnt lgkmcnt(6)
	v_mfma_f32_32x32x16_bf16 v[18:33], v[146:149], v[214:217], v[18:33]
	v_max_f32_e32 v146, v82, v83
	v_max3_f32 v146, v146, v84, v85
	v_max3_f32 v146, v146, v86, v87
	v_max3_f32 v146, v146, v88, v89
	v_max3_f32 v146, v146, v90, v91
	v_max3_f32 v146, v146, v92, v93
	v_max3_f32 v146, v146, v94, v95
	v_max3_f32 v146, v146, v96, v97
	v_max3_f32 v146, v146, v66, v67
	s_waitcnt lgkmcnt(4)
	v_mfma_f32_32x32x16_bf16 v[18:33], v[210:213], v[218:221], v[18:33]
	v_max3_f32 v146, v146, v68, v69
	v_max3_f32 v146, v146, v70, v71
	v_max3_f32 v146, v146, v72, v73
	v_max3_f32 v146, v146, v74, v75
	v_max3_f32 v146, v146, v76, v77
	v_max3_f32 v146, v146, v78, v79
	v_max3_f32 v146, v146, v80, v81
	v_mov_b32_e32 v147, v146
	s_waitcnt lgkmcnt(2)
	v_mfma_f32_32x32x16_bf16 v[18:33], v[152:155], v[222:225], v[18:33]
	s_nop 0
	v_permlane32_swap_b32_e32 v146, v147
	v_max_f32_e32 v146, v146, v147
	v_sub_f32_e32 v147, v146, v150
	v_cmp_ge_f32_e32 vcc, s25, v147
	v_max_f32_e32 v146, v150, v146
	v_sub_f32_e32 v147, v150, v146
	s_cmp_eq_u64 vcc, exec
	v_mul_f32_e32 v147, 0x3e0293ee, v147
	s_waitcnt lgkmcnt(0)
	v_mfma_f32_32x32x16_bf16 v[18:33], v[156:159], v[226:229], v[18:33]
	s_cselect_b64 s[42:43], -1, 0
	v_exp_f32_e32 v147, v147
	s_add_i32 s7, s9, 0x4000
	s_cmp_lg_u32 s6, 2
	s_cselect_b32 s6, s7, 0
	s_add_i32 s10, s6, 0
	v_cndmask_b32_e64 v196, v147, 1.0, s[42:43]
	v_add_u32_e32 v147, s10, v176
	s_waitcnt vmcnt(0)
	s_waitcnt vmcnt(3)
	ds_write_b128 v147, v[130:133]
	s_waitcnt vmcnt(2)
	ds_write_b128 v147, v[134:137] offset:8192
	v_add_u32_e32 v147, s10, v179
	s_waitcnt vmcnt(1)
	ds_write_b128 v147, v[138:141] offset:49152
	v_cmp_gt_f32_e32 vcc, 1.0, v196
	s_waitcnt vmcnt(0)
	ds_write_b128 v147, v[142:145] offset:57344
	s_cbranch_vccz .LBB0_264
	s_and_saveexec_b64 s[6:7], s[38:39]
	ds_write_b32 v190, v196 offset:128
	s_or_b64 exec, exec, s[6:7]
	s_waitcnt lgkmcnt(0)
	v_add_u32_e32 v147, v173, v181
	ds_read_b128 v[152:155], v147 offset:224
	ds_read_b128 v[156:159], v147 offset:192
	ds_read_b128 v[210:213], v147 offset:160
	ds_read_b128 v[214:217], v147 offset:128
	s_waitcnt lgkmcnt(3)
	v_pk_mul_f32 v[14:15], v[14:15], v[152:153]
	s_waitcnt lgkmcnt(2)
	v_pk_mul_f32 v[10:11], v[10:11], v[156:157]
	s_waitcnt lgkmcnt(1)
	v_pk_mul_f32 v[6:7], v[6:7], v[210:211]
	v_pk_mul_f32 v[16:17], v[16:17], v[154:155]
	v_pk_mul_f32 v[12:13], v[12:13], v[158:159]
	v_pk_mul_f32 v[8:9], v[8:9], v[212:213]
	s_waitcnt lgkmcnt(0)
	v_pk_mul_f32 v[4:5], v[4:5], v[216:217]
	v_pk_mul_f32 v[2:3], v[2:3], v[214:215]
	v_pk_mul_f32 v[62:63], v[62:63], v[152:153]
	v_pk_mul_f32 v[58:59], v[58:59], v[156:157]
	v_pk_mul_f32 v[54:55], v[54:55], v[210:211]
	v_pk_mul_f32 v[64:65], v[64:65], v[154:155]
	v_pk_mul_f32 v[60:61], v[60:61], v[158:159]
	v_pk_mul_f32 v[56:57], v[56:57], v[212:213]
	v_pk_mul_f32 v[52:53], v[52:53], v[216:217]
	v_pk_mul_f32 v[50:51], v[50:51], v[214:215]
	v_pk_mul_f32 v[46:47], v[46:47], v[152:153]
	v_pk_mul_f32 v[42:43], v[42:43], v[156:157]
	v_pk_mul_f32 v[38:39], v[38:39], v[210:211]
	v_pk_mul_f32 v[48:49], v[48:49], v[154:155]
	v_pk_mul_f32 v[44:45], v[44:45], v[158:159]
	v_pk_mul_f32 v[40:41], v[40:41], v[212:213]
	v_pk_mul_f32 v[36:37], v[36:37], v[216:217]
	v_pk_mul_f32 v[34:35], v[34:35], v[214:215]
	v_pk_mul_f32 v[30:31], v[30:31], v[152:153]
	v_pk_mul_f32 v[26:27], v[26:27], v[156:157]
	v_pk_mul_f32 v[22:23], v[22:23], v[210:211]
	v_pk_mul_f32 v[32:33], v[32:33], v[154:155]
	v_pk_mul_f32 v[28:29], v[28:29], v[158:159]
	v_pk_mul_f32 v[24:25], v[24:25], v[212:213]
	v_pk_mul_f32 v[20:21], v[20:21], v[216:217]
	v_pk_mul_f32 v[18:19], v[18:19], v[214:215]
; __device__ __forceinline__ void partialSM(f32x16& p0, f32x16& p1, float& m_reg, float& mn, float& alpha) {
;     ...
;   float mnC = -mn * C;
; #pragma unroll
;   for (int r = 0; r < 16; ++r) p0[r] = fmaf(p0[r], C, mnC);
; #pragma unroll
;   for (int r = 0; r < 16; ++r) p1[r] = fmaf(p1[r], C, mnC);
; #pragma unroll
;   for (int r = 0; r < 16; ++r) p0[r] = __builtin_amdgcn_exp2f(p0[r]);
.LBB0_264:
	v_cndmask_b32_e64 v209, v146, v150, s[42:43]
	v_mul_f32_e32 v154, 0xbe0293ee, v209
	s_add_i32 s4, s4, 2
	v_fmamk_f32 v82, v82, 0x3e0293ee, v154
	v_fmamk_f32 v83, v83, 0x3e0293ee, v154
	v_fmamk_f32 v84, v84, 0x3e0293ee, v154
	v_fmamk_f32 v85, v85, 0x3e0293ee, v154
	v_fmamk_f32 v86, v86, 0x3e0293ee, v154
	v_fmamk_f32 v87, v87, 0x3e0293ee, v154
	v_fmamk_f32 v88, v88, 0x3e0293ee, v154
	v_fmamk_f32 v89, v89, 0x3e0293ee, v154
	v_fmamk_f32 v90, v90, 0x3e0293ee, v154
	v_fmamk_f32 v91, v91, 0x3e0293ee, v154
	v_fmamk_f32 v92, v92, 0x3e0293ee, v154
	v_fmamk_f32 v93, v93, 0x3e0293ee, v154
	v_fmamk_f32 v94, v94, 0x3e0293ee, v154
	v_fmamk_f32 v95, v95, 0x3e0293ee, v154
	v_fmamk_f32 v96, v96, 0x3e0293ee, v154
	v_fmamk_f32 v97, v97, 0x3e0293ee, v154
	v_fmamk_f32 v155, v66, 0x3e0293ee, v154
	v_fmamk_f32 v156, v67, 0x3e0293ee, v154
	v_fmamk_f32 v157, v68, 0x3e0293ee, v154
	v_fmamk_f32 v158, v69, 0x3e0293ee, v154
	v_fmamk_f32 v159, v70, 0x3e0293ee, v154
	v_fmamk_f32 v160, v71, 0x3e0293ee, v154
	v_fmamk_f32 v161, v72, 0x3e0293ee, v154
	v_fmamk_f32 v198, v73, 0x3e0293ee, v154
	v_fmamk_f32 v199, v74, 0x3e0293ee, v154
	v_fmamk_f32 v200, v75, 0x3e0293ee, v154
	v_fmamk_f32 v201, v76, 0x3e0293ee, v154
	v_fmamk_f32 v202, v77, 0x3e0293ee, v154
	v_fmamk_f32 v203, v78, 0x3e0293ee, v154
	v_fmamk_f32 v204, v79, 0x3e0293ee, v154
	v_fmamk_f32 v205, v80, 0x3e0293ee, v154
	v_fmac_f32_e32 v154, 0x3e0293ee, v81
	v_exp_f32_e32 v206, v82
	v_exp_f32_e32 v207, v83
	v_exp_f32_e32 v212, v84
	v_exp_f32_e32 v213, v85
	v_exp_f32_e32 v214, v86
	v_exp_f32_e32 v215, v87
	v_exp_f32_e32 v216, v88
	v_exp_f32_e32 v217, v89
	v_exp_f32_e32 v218, v90
	v_exp_f32_e32 v219, v91
	v_exp_f32_e32 v220, v92
	v_exp_f32_e32 v221, v93
	v_exp_f32_e32 v222, v94
	v_exp_f32_e32 v223, v95
	v_exp_f32_e32 v224, v96
	v_exp_f32_e32 v225, v97
	s_waitcnt lgkmcnt(0)
	s_barrier
; #define SBAR() __builtin_amdgcn_sched_barrier(0)
; #define SLOAD(i, t) do { const long rb_ = TROW(t); const char* vt_ = (const char*)Vh + rb_ * (LDK * 2); const char* kt_ = (const char*)Kh + rb_ * (LDK * 2); \
;     sr_[i].vs0 = *(const bf16x8*)(vt_ + lo0); sr_[i].vs1 = *(const bf16x8*)(vt_ + lo0 + 32 * LDK * 2); \
;     sr_[i].ks0 = *(const bf16x8*)(kt_ + lo0); sr_[i].ks1 = *(const bf16x8*)(kt_ + lo0 + 32 * LDK * 2); } while (0)
; __device__ __forceinline__ void finishSM(f32x16& p0, f32x16& p1, float alpha, float& l_reg, bf16x8& pa0, bf16x8& pa1, bf16x8& pa2, bf16x8& pa3) {
; #pragma unroll
;   for (int r = 0; r < 16; ++r) p1[r] = __builtin_amdgcn_exp2f(p1[r]);
;   float ps = 0;
; #pragma unroll
;   for (int r = 0; r < 16; ++r) ps += p0[r];
; #pragma unroll
;   for (int r = 0; r < 16; ++r) ps += p1[r];
;   { auto rr = __builtin_amdgcn_permlane32_swap(__float_as_uint(ps), __float_as_uint(ps), false, false);
;     ps = __uint_as_float(rr[0]) + __uint_as_float(rr[1]); }
;   l_reg = l_reg * alpha + ps;
;     ...
;   PK4(p0, 0, pa0); PK4(p0, 8, pa1); PK4(p1, 0, pa2); PK4(p1, 8, pa3);
; template <bool META>
; __device__ __forceinline__ void attn_unit(const bf16_t* Q, bf16_t* Oo, const bf16_t* __restrict__ Kb, const bf16_t* __restrict__ Vb, int b, int kvh, int h, int qb, char* lds, const int tid, const float* qn, const float* RT) {
;     ...
;     SBAR(); qkt(pA0, pA1, (bf16_t*)((char*)K_lds + bn * SHM_K), qr, r32, hi);
;     if (j + 1 == NT - 1) mask_last(pA0, pA1);
;     finishSM(pB0, pB1, alB, l_reg, pa0, pa1, pa2, pa3); SBAR();
;     if (j + 2 < NT) SLOAD(SE, j + 2);
	v_add_u32_e32 v70, s10, v182
	ds_read_b128 v[66:69], v70 offset:49152
	ds_read_b128 v[82:85], v70 offset:57344
	v_add_u32_e32 v150, s10, v183
	ds_read_b128 v[146:149], v150 offset:49152
	ds_read_b128 v[150:153], v150 offset:57344
	v_exp_f32_e32 v155, v155
	s_waitcnt lgkmcnt(3)
	v_mfma_f32_32x32x16_bf16 v[66:81], v[66:69], v[98:101], 0
	v_exp_f32_e32 v156, v156
	v_exp_f32_e32 v157, v157
	v_exp_f32_e32 v158, v158
	v_exp_f32_e32 v159, v159
	v_exp_f32_e32 v160, v160
	v_exp_f32_e32 v161, v161
	v_exp_f32_e32 v198, v198
	s_waitcnt lgkmcnt(2)
	v_mfma_f32_32x32x16_bf16 v[82:97], v[82:85], v[98:101], 0
	v_exp_f32_e32 v199, v199
	v_exp_f32_e32 v200, v200
	v_exp_f32_e32 v201, v201
	v_exp_f32_e32 v202, v202
	v_exp_f32_e32 v203, v203
	v_exp_f32_e32 v204, v204
	v_exp_f32_e32 v205, v205
	s_waitcnt lgkmcnt(1)
	v_mfma_f32_32x32x16_bf16 v[66:81], v[146:149], v[102:105], v[66:81]
	v_exp_f32_e32 v226, v154
	v_cvt_pk_bf16_f32 v154, v155, v156
	s_waitcnt lgkmcnt(0)
	v_mfma_f32_32x32x16_bf16 v[82:97], v[150:153], v[102:105], v[82:97]
	v_add_u32_e32 v150, s10, v184
	ds_read_b128 v[146:149], v150 offset:49152
	ds_read_b128 v[150:153], v150 offset:57344
	s_waitcnt lgkmcnt(1)
	v_mfma_f32_32x32x16_bf16 v[66:81], v[146:149], v[106:109], v[66:81]
	s_waitcnt lgkmcnt(0)
	v_mfma_f32_32x32x16_bf16 v[82:97], v[150:153], v[106:109], v[82:97]
	v_add_u32_e32 v150, s10, v185
	ds_read_b128 v[146:149], v150 offset:49152
	ds_read_b128 v[150:153], v150 offset:57344
	s_waitcnt lgkmcnt(1)
	v_mfma_f32_32x32x16_bf16 v[66:81], v[146:149], v[110:113], v[66:81]
	s_waitcnt lgkmcnt(0)
	v_mfma_f32_32x32x16_bf16 v[82:97], v[150:153], v[110:113], v[82:97]
	v_add_u32_e32 v150, s10, v186
	ds_read_b128 v[146:149], v150 offset:49152
	ds_read_b128 v[150:153], v150 offset:57344
	s_waitcnt lgkmcnt(1)
	v_mfma_f32_32x32x16_bf16 v[66:81], v[146:149], v[114:117], v[66:81]
	s_waitcnt lgkmcnt(0)
	v_mfma_f32_32x32x16_bf16 v[82:97], v[150:153], v[114:117], v[82:97]
	v_add_u32_e32 v150, s10, v187
	ds_read_b128 v[146:149], v150 offset:49152
	ds_read_b128 v[150:153], v150 offset:57344
	s_waitcnt lgkmcnt(1)
	v_mfma_f32_32x32x16_bf16 v[66:81], v[146:149], v[118:121], v[66:81]
	s_waitcnt lgkmcnt(0)
	v_mfma_f32_32x32x16_bf16 v[82:97], v[150:153], v[118:121], v[82:97]
	v_add_u32_e32 v150, s10, v188
	ds_read_b128 v[146:149], v150 offset:49152
	ds_read_b128 v[150:153], v150 offset:57344
	s_waitcnt lgkmcnt(1)
	v_mfma_f32_32x32x16_bf16 v[66:81], v[146:149], v[122:125], v[66:81]
	s_waitcnt lgkmcnt(0)
	v_mfma_f32_32x32x16_bf16 v[82:97], v[150:153], v[122:125], v[82:97]
	v_add_u32_e32 v150, s10, v189
	ds_read_b128 v[146:149], v150 offset:49152
	ds_read_b128 v[150:153], v150 offset:57344
	s_waitcnt lgkmcnt(1)
	v_mfma_f32_32x32x16_bf16 v[66:81], v[146:149], v[126:129], v[66:81]
	v_add_f32_e32 v146, v207, v206
	v_add_f32_e32 v146, v212, v146
	v_add_f32_e32 v146, v213, v146
	v_add_f32_e32 v146, v214, v146
	v_add_f32_e32 v146, v215, v146
	v_add_f32_e32 v146, v216, v146
	v_add_f32_e32 v146, v217, v146
	v_add_f32_e32 v146, v218, v146
	v_add_f32_e32 v146, v219, v146
	v_add_f32_e32 v146, v220, v146
	v_add_f32_e32 v146, v221, v146
	v_add_f32_e32 v146, v222, v146
	v_add_f32_e32 v146, v223, v146
	v_add_f32_e32 v146, v224, v146
	v_add_f32_e32 v146, v225, v146
	v_add_f32_e32 v146, v155, v146
	v_add_f32_e32 v146, v156, v146
	v_add_f32_e32 v146, v157, v146
	v_add_f32_e32 v146, v158, v146
	v_add_f32_e32 v146, v159, v146
	v_add_f32_e32 v146, v160, v146
	v_add_f32_e32 v146, v161, v146
	v_add_f32_e32 v146, v198, v146
	v_add_f32_e32 v146, v199, v146
	v_add_f32_e32 v146, v200, v146
	s_waitcnt lgkmcnt(0)
	v_mfma_f32_32x32x16_bf16 v[82:97], v[150:153], v[126:129], v[82:97]
	v_add_f32_e32 v146, v201, v146
	v_add_f32_e32 v146, v202, v146
	v_add_f32_e32 v146, v203, v146
	v_add_f32_e32 v146, v204, v146
	v_add_f32_e32 v146, v205, v146
	v_add_f32_e32 v210, v226, v146
	v_mov_b32_e32 v211, v210
	v_cvt_pk_bf16_f32 v146, v206, v207
	v_cvt_pk_bf16_f32 v147, v212, v213
	v_cvt_pk_bf16_f32 v148, v214, v215
	v_cvt_pk_bf16_f32 v149, v216, v217
	v_cvt_pk_bf16_f32 v150, v218, v219
	v_cvt_pk_bf16_f32 v151, v220, v221
	v_cvt_pk_bf16_f32 v152, v222, v223
	v_cvt_pk_bf16_f32 v153, v224, v225
	v_cvt_pk_bf16_f32 v155, v157, v158
	v_cvt_pk_bf16_f32 v156, v159, v160
	v_cvt_pk_bf16_f32 v157, v161, v198
	v_cvt_pk_bf16_f32 v158, v199, v200
	v_cvt_pk_bf16_f32 v159, v201, v202
	v_cvt_pk_bf16_f32 v160, v203, v204
	v_cvt_pk_bf16_f32 v161, v205, v226
	v_permlane32_swap_b32_e32 v210, v211
	v_permlane32_swap_b32_e32 v146, v148
	v_permlane32_swap_b32_e32 v147, v149
	v_permlane32_swap_b32_e32 v150, v152
	v_permlane32_swap_b32_e32 v151, v153
	v_permlane32_swap_b32_e32 v154, v156
	v_permlane32_swap_b32_e32 v155, v157
	v_permlane32_swap_b32_e32 v158, v160
	v_permlane32_swap_b32_e32 v159, v161
	s_andn2_b64 vcc, exec, s[0:1]
	s_cbranch_vccnz .LBB0_266
	s_add_u32 s0, s90, 64
	s_addc_u32 s1, s91, 0
	s_cmpk_lt_u32 s4, 0xfe
	s_cselect_b32 s1, s1, s44
	s_cselect_b32 s0, s0, s31
	s_lshl_b64 s[0:1], s[0:1], 9
	s_add_u32 s16, s12, s0
	s_addc_u32 s17, s13, s1
	s_add_u32 s18, s14, s0
	s_addc_u32 s19, s15, s1
	global_load_dwordx4 v[130:133], v166, s[16:17]
	global_load_dwordx4 v[134:137], v238, s[16:17]
	global_load_dwordx4 v[138:141], v166, s[18:19]
	global_load_dwordx4 v[142:145], v238, s[18:19]

; #define SBAR() __builtin_amdgcn_sched_barrier(0)
; __device__ __forceinline__ void finishSM(f32x16& p0, f32x16& p1, float alpha, float& l_reg, bf16x8& pa0, bf16x8& pa1, bf16x8& pa2, bf16x8& pa3) {
; #pragma unroll
;   for (int r = 0; r < 16; ++r) p1[r] = __builtin_amdgcn_exp2f(p1[r]);
;   float ps = 0;
; #pragma unroll
;   for (int r = 0; r < 16; ++r) ps += p0[r];
; #pragma unroll
;   for (int r = 0; r < 16; ++r) ps += p1[r];
;   { auto rr = __builtin_amdgcn_permlane32_swap(__float_as_uint(ps), __float_as_uint(ps), false, false);
;     ps = __uint_as_float(rr[0]) + __uint_as_float(rr[1]); }
;   l_reg = l_reg * alpha + ps;
;     ...
;   PK4(p0, 0, pa0); PK4(p0, 8, pa1); PK4(p1, 0, pa2); PK4(p1, 8, pa3);
; template <bool META>
; __device__ __forceinline__ void attn_unit(const bf16_t* Q, bf16_t* Oo, const bf16_t* __restrict__ Kb, const bf16_t* __restrict__ Vb, int b, int kvh, int h, int qb, char* lds, const int tid, const float* qn, const float* RT) {
;     ...
;   { const int bl = bc == 0 ? 2 : bc - 1;
;     finishSM(pA0, pA1, alA, l_reg, pa0, pa1, pa2, pa3); SBAR();
;     pv_d0(o, vb0 + bl * (int)SHM_V, pa0, pa1, pa2, pa3); }
;   if (hi == 0) li_l[r32] = l_reg; asm volatile("s_waitcnt lgkmcnt(0)" ::: "memory");
.LBB0_272:
	s_mov_b32 s12, s5
	s_mov_b32 s13, s5
	s_mov_b32 s14, s5
	s_mov_b32 s15, s5
	s_mov_b32 s16, s5
	s_mov_b32 s17, s5
	s_mov_b32 s18, s5
	s_mov_b32 s19, s5
	v_add_f32_e32 v66, 0, v146
	v_add_f32_e32 v66, v147, v66
	v_add_f32_e32 v66, v148, v66
	v_add_f32_e32 v66, v159, v66
	v_add_f32_e32 v66, v160, v66
	v_add_f32_e32 v66, v209, v66
	v_add_f32_e32 v66, v149, v66
	v_add_f32_e32 v66, v161, v66
	v_add_f32_e32 v66, v151, v66
	v_add_f32_e32 v66, v153, v66
	v_add_f32_e32 v66, v154, v66
	v_add_f32_e32 v66, v157, v66
	v_exp_f32_e32 v76, v144
	v_add_f32_e32 v66, v152, v66
	v_exp_f32_e32 v77, v145
	v_add_f32_e32 v66, v155, v66
	v_exp_f32_e32 v78, v142
	v_add_f32_e32 v66, v156, v66
	v_exp_f32_e32 v79, v143
	v_add_f32_e32 v66, v158, v66
	v_exp_f32_e32 v80, v140
	v_add_f32_e32 v66, v76, v66
	v_exp_f32_e32 v81, v141
	v_add_f32_e32 v66, v77, v66
	v_exp_f32_e32 v82, v138
	v_add_f32_e32 v66, v78, v66
	v_exp_f32_e32 v83, v139
	v_add_f32_e32 v66, v79, v66
	v_exp_f32_e32 v84, v136
	v_add_f32_e32 v66, v80, v66
	v_exp_f32_e32 v85, v137
	v_add_f32_e32 v66, v81, v66
	v_exp_f32_e32 v86, v134
	v_add_f32_e32 v66, v82, v66
	v_exp_f32_e32 v87, v135
	v_add_f32_e32 v66, v83, v66
	v_exp_f32_e32 v88, v132
	v_add_f32_e32 v66, v84, v66
	v_exp_f32_e32 v89, v133
	v_add_f32_e32 v66, v85, v66
	v_exp_f32_e32 v91, v130
	v_add_f32_e32 v66, v86, v66
	v_exp_f32_e32 v92, v131
	v_add_f32_e32 v66, v87, v66
	v_add_f32_e32 v66, v88, v66
	v_add_f32_e32 v66, v89, v66
	v_add_f32_e32 v66, v91, v66
	v_add_f32_e32 v66, v92, v66
	v_mov_b32_e32 v67, v66
	s_nop 1
	v_permlane32_swap_b32_e32 v66, v67
	v_cvt_pk_bf16_f32 v68, v146, v147
	v_cvt_pk_bf16_f32 v69, v148, v159
	v_cvt_pk_bf16_f32 v70, v160, v209
	v_cvt_pk_bf16_f32 v71, v149, v161
	v_cvt_pk_bf16_f32 v72, v151, v153
	v_cvt_pk_bf16_f32 v73, v154, v157
	v_cvt_pk_bf16_f32 v74, v152, v155
	v_cvt_pk_bf16_f32 v75, v156, v158
	v_cvt_pk_bf16_f32 v76, v76, v77
	v_cvt_pk_bf16_f32 v77, v78, v79
	v_cvt_pk_bf16_f32 v78, v80, v81
	v_cvt_pk_bf16_f32 v79, v82, v83
	v_cvt_pk_bf16_f32 v80, v84, v85
	v_cvt_pk_bf16_f32 v81, v86, v87
	v_cvt_pk_bf16_f32 v82, v88, v89
	v_cvt_pk_bf16_f32 v83, v91, v92
	v_permlane32_swap_b32_e32 v68, v70
	v_permlane32_swap_b32_e32 v69, v71
	v_permlane32_swap_b32_e32 v72, v74
	v_permlane32_swap_b32_e32 v73, v75
	v_permlane32_swap_b32_e32 v76, v78
	v_permlane32_swap_b32_e32 v77, v79
	v_permlane32_swap_b32_e32 v80, v82
	v_permlane32_swap_b32_e32 v81, v83
	s_addk_i32 s8, 0xc000
	s_cmp_lg_u32 s28, 0
	s_cselect_b32 s0, s8, 0x8000
	v_add_u32_e32 v88, s0, v178
	ds_read_b64_tr_b16 v[84:85], v88 offset:0
	ds_read_b64_tr_b16 v[86:87], v88 offset:0x800
	ds_read_b64_tr_b16 v[92:93], v88 offset:0x1000
	ds_read_b64_tr_b16 v[94:95], v88 offset:0x1800
	ds_read_b64_tr_b16 v[96:97], v88 offset:0x2000
	ds_read_b64_tr_b16 v[98:99], v88 offset:0x2800
	ds_read_b64_tr_b16 v[100:101], v88 offset:0x3000
	ds_read_b64_tr_b16 v[102:103], v88 offset:0x3800
	s_waitcnt lgkmcnt(0)
	s_nop 0
	v_mfma_f32_32x32x16_bf16 v[2:17], v[68:71], v[84:87], v[2:17]
	ds_read_b64_tr_b16 v[84:85], v88 offset:0x200
	ds_read_b64_tr_b16 v[86:87], v88 offset:0xa00
	v_mfma_f32_32x32x16_bf16 v[2:17], v[72:75], v[92:95], v[2:17]
	ds_read_b64_tr_b16 v[92:93], v88 offset:0x1200
	ds_read_b64_tr_b16 v[94:95], v88 offset:0x1a00
	v_mfma_f32_32x32x16_bf16 v[2:17], v[76:79], v[96:99], v[2:17]
	ds_read_b64_tr_b16 v[96:97], v88 offset:0x2200
	ds_read_b64_tr_b16 v[98:99], v88 offset:0x2a00
	v_mfma_f32_32x32x16_bf16 v[2:17], v[80:83], v[100:103], v[2:17]
	ds_read_b64_tr_b16 v[100:101], v88 offset:0x3200
	ds_read_b64_tr_b16 v[102:103], v88 offset:0x3a00
	s_waitcnt lgkmcnt(0)
	v_mfma_f32_32x32x16_bf16 v[50:65], v[68:71], v[84:87], v[50:65]
	ds_read_b64_tr_b16 v[84:85], v88 offset:0x400
	ds_read_b64_tr_b16 v[86:87], v88 offset:0xc00
	v_mfma_f32_32x32x16_bf16 v[50:65], v[72:75], v[92:95], v[50:65]
	ds_read_b64_tr_b16 v[92:93], v88 offset:0x1400
	ds_read_b64_tr_b16 v[94:95], v88 offset:0x1c00
	v_mfma_f32_32x32x16_bf16 v[50:65], v[76:79], v[96:99], v[50:65]
	ds_read_b64_tr_b16 v[96:97], v88 offset:0x2400
	ds_read_b64_tr_b16 v[98:99], v88 offset:0x2c00
	v_mfma_f32_32x32x16_bf16 v[50:65], v[80:83], v[100:103], v[50:65]
	ds_read_b64_tr_b16 v[100:101], v88 offset:0x3400
	ds_read_b64_tr_b16 v[102:103], v88 offset:0x3c00
	s_waitcnt lgkmcnt(0)
	v_mfma_f32_32x32x16_bf16 v[34:49], v[68:71], v[84:87], v[34:49]
	ds_read_b64_tr_b16 v[84:85], v88 offset:0x600
	ds_read_b64_tr_b16 v[86:87], v88 offset:0xe00
	v_mfma_f32_32x32x16_bf16 v[34:49], v[72:75], v[92:95], v[34:49]
	ds_read_b64_tr_b16 v[92:93], v88 offset:0x1600
	ds_read_b64_tr_b16 v[94:95], v88 offset:0x1e00
	v_mfma_f32_32x32x16_bf16 v[34:49], v[76:79], v[96:99], v[34:49]
	ds_read_b64_tr_b16 v[96:97], v88 offset:0x2600
	ds_read_b64_tr_b16 v[98:99], v88 offset:0x2e00
	v_mfma_f32_32x32x16_bf16 v[34:49], v[80:83], v[100:103], v[34:49]
	ds_read_b64_tr_b16 v[100:101], v88 offset:0x3600
	ds_read_b64_tr_b16 v[102:103], v88 offset:0x3e00
	s_waitcnt lgkmcnt(0)
	v_mfma_f32_32x32x16_bf16 v[18:33], v[68:71], v[84:87], v[18:33]
	v_mfma_f32_32x32x16_bf16 v[18:33], v[72:75], v[92:95], v[18:33]
	v_mfma_f32_32x32x16_bf16 v[18:33], v[76:79], v[96:99], v[18:33]
	v_mfma_f32_32x32x16_bf16 v[18:33], v[80:83], v[100:103], v[18:33]
	s_and_saveexec_b64 s[0:1], s[38:39]
	s_cbranch_execz .LBB0_258
	v_add_f32_e32 v66, v66, v67
	v_fmac_f32_e32 v66, v0, v230
	ds_write_b32 v190, v66
	s_branch .LBB0_258
